# Q and K GEMM epilogues: sum-of-squares lines of all row groups touched up front
# speedup vs baseline: 1.0803x; 1.0013x over previous
; #define PG8_STAGE(bufoff, gbase, voff) do { _Pragma("unroll") for (int _i = 0; _i < 2; ++_i) { const char* _gb = (const char*)(gbase) + (size_t)_i * (voff##_q); asm volatile("" : "+s"(_gb)); \
;         __builtin_amdgcn_global_load_lds((const unsigned*)(_gb + (voff)), (LAS unsigned*)(lds + (bufoff) + ldsw + _i * 8192), 16, 0, 0); } } while (0)
; #define PG8_LDA(dst, b, h) do { _Pragma("unroll") for (int m = 0; m < 4; ++m) _Pragma("unroll") for (int k = 0; k < 2; ++k) dst[m][k] = *(const LAS bf16x8*)(lds + PG8_SA(b, h) + aoff + m * 2048 + k * 1024); } while (0)
; #define PG8_LDB(dst, b, h) do { _Pragma("unroll") for (int n = 0; n < 2; ++n) _Pragma("unroll") for (int k = 0; k < 2; ++k) dst[n][k] = *(const LAS bf16x8*)(lds + PG8_SB(b, h) + boff + n * 2048 + k * 1024); } while (0)
; #define PG8_MMA(ai, bj, At, Bt) do { __builtin_amdgcn_s_setprio(1); _Pragma("unroll") for (int m = 0; m < 4; ++m) _Pragma("unroll") for (int n = 0; n < 2; ++n) _Pragma("unroll") for (int k = 0; k < 2; ++k) \
;         acc[ai][bj][m][n] = __builtin_amdgcn_mfma_f32_16x16x32_bf16(Bt[n][k], At[m][k], acc[ai][bj][m][n], 0, 0, 0); __builtin_amdgcn_s_setprio(0); } while (0)
; #define PG8_WAIT_L(n) asm volatile("s_waitcnt lgkmcnt(" #n ")" ::: "memory")
; #define PG8_BAR __builtin_amdgcn_s_barrier()
; template <class Epi, class Sched>
; __device__ __forceinline__ void gemm_phase(int wv, LAS unsigned char* lds, const Gemm g, const Sched& S, const Epi& E) { LIDS
;     ...
;         for (int t = 0; t < nt; t += 2) {
;             const bool last = (t == nt - 2);
;             const char* a1 = cA + (size_t)(t + 1) * kstepA;
;             const char* a2 = last ? nA : cA + (size_t)(t + 2) * kstepA; const char* b2 = last ? nB : cB + (size_t)(t + 2) * kstepB;
;             const char* a3 = a2 + kstepA; const char* b3 = b2 + kstepB;
;             asm volatile("" : "+s"(a1), "+s"(a2), "+s"(b2), "+s"(a3), "+s"(b3));
;             PG8_LDB(B0, 0, 0); PG8_SCHED; PG8_LDA(At, 0, 0); PG8_STAGE(PG8_SA(1, 1), a1 + hstepA, voffA);
;             PG8_WAIT_L(8); PG8_BAR; PG8_WAIT_L(0); PG8_MMA(0, 0, At, B0); PG8_BAR; PG8_SCHED;
;             PG8_LDB(B1, 0, 1); PG8_STAGE(PG8_SB(0, 0), b2, voffB);
;             PG8_BAR; PG8_WAIT_L(0); PG8_MMA(0, 1, At, B1); PG8_BAR;
;             PG8_LDA(At, 0, 1); PG8_STAGE(PG8_SA(0, 0), a2, voffA);
;             PG8_BAR; PG8_WAIT_L(0); PG8_MMA(1, 0, At, B0); PG8_BAR; PG8_SCHED;
.LBB0_123:
	s_add_u32 s20, s68, 0x80
	s_addc_u32 s21, s69, 0
	s_add_u32 s68, s68, 0x100
	s_addc_u32 s69, s69, 0
	s_cmp_eq_u32 s18, 4
	s_cselect_b32 s84, s9, s68
	s_cselect_b32 s85, s7, s69
	s_cselect_b32 s89, s11, s17
	s_cselect_b32 s88, s13, s16
	s_add_u32 s86, s84, 0x80
	s_addc_u32 s87, s85, 0
	s_add_u32 s78, s88, 0x80
	s_addc_u32 s79, s89, 0
	s_add_i32 s19, 16, 0x10000
	v_add_u32_e32 v144, s19, v149
	ds_read_b128 v[128:131], v144
	ds_read_b128 v[132:135], v144 offset:1024
	ds_read_b128 v[140:143], v144 offset:2048
	ds_read_b128 v[144:147], v144 offset:3072
	s_add_u32 s22, s20, 0x100000
	s_addc_u32 s23, s21, 0
	s_add_i32 m0, s91, 0xc000
	s_add_u32 s20, s20, 0x180000
	ds_read_b128 v[152:155], v150
	ds_read_b128 v[156:159], v150 offset:1024
	ds_read_b128 v[160:163], v150 offset:2048
	ds_read_b128 v[164:167], v150 offset:3072
	ds_read_b128 v[168:171], v150 offset:4096
	ds_read_b128 v[172:175], v150 offset:5120
	ds_read_b128 v[194:197], v150 offset:6144
	ds_read_b128 v[198:201], v150 offset:7168
	s_addc_u32 s21, s21, 0
	v_lshl_add_u64 v[178:179], s[22:23], 0, v[136:137]
	global_load_lds_dwordx4 v[178:179], off
	s_add_i32 m0, s91, 0xe000
	v_lshl_add_u64 v[178:179], s[20:21], 0, v[136:137]
	global_load_lds_dwordx4 v[178:179], off
	s_waitcnt lgkmcnt(8)
	s_barrier
	s_waitcnt lgkmcnt(0)
	s_setprio 1
	s_waitcnt lgkmcnt(0)
	v_mfma_f32_16x16x32_bf16 v[124:127], v[128:131], v[152:155], v[124:127]
	v_mfma_f32_16x16x32_bf16 v[120:123], v[140:143], v[152:155], v[120:123]
	v_mfma_f32_16x16x32_bf16 v[108:111], v[128:131], v[160:163], v[108:111]
	v_mfma_f32_16x16x32_bf16 v[104:107], v[140:143], v[160:163], v[104:107]
	v_mfma_f32_16x16x32_bf16 v[92:95], v[128:131], v[168:171], v[92:95]
	v_mfma_f32_16x16x32_bf16 v[88:91], v[140:143], v[168:171], v[88:91]
	v_mfma_f32_16x16x32_bf16 v[76:79], v[128:131], v[194:197], v[76:79]
	v_mfma_f32_16x16x32_bf16 v[72:75], v[140:143], v[194:197], v[72:75]
	v_mfma_f32_16x16x32_bf16 v[124:127], v[132:135], v[156:159], v[124:127]
	v_mfma_f32_16x16x32_bf16 v[120:123], v[144:147], v[156:159], v[120:123]
	v_mfma_f32_16x16x32_bf16 v[108:111], v[132:135], v[164:167], v[108:111]
	v_mfma_f32_16x16x32_bf16 v[104:107], v[144:147], v[164:167], v[104:107]
	v_mfma_f32_16x16x32_bf16 v[92:95], v[132:135], v[172:175], v[92:95]
	v_mfma_f32_16x16x32_bf16 v[88:91], v[144:147], v[172:175], v[88:91]
	v_mfma_f32_16x16x32_bf16 v[76:79], v[132:135], v[198:201], v[76:79]
	v_mfma_f32_16x16x32_bf16 v[72:75], v[144:147], v[198:201], v[72:75]
	s_setprio 0
	s_barrier
	s_add_i32 s22, 16, 0x14000
	v_add_u32_e32 v151, s22, v149
	s_mov_b64 s[20:21], s[88:89]
	ds_read_b128 v[202:205], v151
	ds_read_b128 v[206:209], v151 offset:1024
	ds_read_b128 v[218:221], v151 offset:2048
	ds_read_b128 v[222:225], v151 offset:3072
	s_add_i32 s19, s19, s90
	v_lshl_add_u64 v[178:179], s[20:21], 0, v[138:139]
	s_add_u32 s20, s88, 0x10000
	s_mov_b32 m0, s19
	s_addc_u32 s21, s89, 0
	global_load_lds_dwordx4 v[178:179], off
	s_add_i32 m0, s19, 0x2000
	v_lshl_add_u64 v[178:179], s[20:21], 0, v[138:139]
	global_load_lds_dwordx4 v[178:179], off
	s_barrier
	s_waitcnt lgkmcnt(0)
	s_setprio 1
	s_waitcnt lgkmcnt(0)
	v_mfma_f32_16x16x32_bf16 v[116:119], v[202:205], v[152:155], v[116:119]
	v_mfma_f32_16x16x32_bf16 v[112:115], v[218:221], v[152:155], v[112:115]
	v_mfma_f32_16x16x32_bf16 v[100:103], v[202:205], v[160:163], v[100:103]
	v_mfma_f32_16x16x32_bf16 v[96:99], v[218:221], v[160:163], v[96:99]
	v_mfma_f32_16x16x32_bf16 v[84:87], v[202:205], v[168:171], v[84:87]
	v_mfma_f32_16x16x32_bf16 v[80:83], v[218:221], v[168:171], v[80:83]
	v_mfma_f32_16x16x32_bf16 v[68:71], v[202:205], v[194:197], v[68:71]
	v_mfma_f32_16x16x32_bf16 v[64:67], v[218:221], v[194:197], v[64:67]
	v_mfma_f32_16x16x32_bf16 v[116:119], v[206:209], v[156:159], v[116:119]
	v_mfma_f32_16x16x32_bf16 v[112:115], v[222:225], v[156:159], v[112:115]
	v_mfma_f32_16x16x32_bf16 v[100:103], v[206:209], v[164:167], v[100:103]
	v_mfma_f32_16x16x32_bf16 v[96:99], v[222:225], v[164:167], v[96:99]
	v_mfma_f32_16x16x32_bf16 v[84:87], v[206:209], v[172:175], v[84:87]
	v_mfma_f32_16x16x32_bf16 v[80:83], v[222:225], v[172:175], v[80:83]
	v_mfma_f32_16x16x32_bf16 v[68:71], v[206:209], v[198:201], v[68:71]
	v_mfma_f32_16x16x32_bf16 v[64:67], v[222:225], v[198:201], v[64:67]
	s_setprio 0
	s_mov_b64 s[20:21], s[84:85]
	s_barrier
	ds_read_b128 v[152:155], v150 offset:16384
	ds_read_b128 v[156:159], v150 offset:17408
	ds_read_b128 v[160:163], v150 offset:18432
	ds_read_b128 v[164:167], v150 offset:19456
	ds_read_b128 v[168:171], v150 offset:20480
	ds_read_b128 v[172:175], v150 offset:21504
	ds_read_b128 v[194:197], v150 offset:22528
	ds_read_b128 v[198:201], v150 offset:23552
	s_mov_b32 m0, s91
	v_lshl_add_u64 v[178:179], s[20:21], 0, v[136:137]
	s_add_u32 s20, s84, 0x80000
	s_addc_u32 s21, s85, 0
	global_load_lds_dwordx4 v[178:179], off
	s_mov_b32 m0, s94
	v_lshl_add_u64 v[178:179], s[20:21], 0, v[136:137]
	global_load_lds_dwordx4 v[178:179], off
	s_barrier
	s_waitcnt lgkmcnt(0)
	s_setprio 1
	s_waitcnt lgkmcnt(0)
	v_mfma_f32_16x16x32_bf16 v[60:63], v[128:131], v[152:155], v[60:63]
	v_mfma_f32_16x16x32_bf16 v[56:59], v[140:143], v[152:155], v[56:59]
	v_mfma_f32_16x16x32_bf16 v[44:47], v[128:131], v[160:163], v[44:47]
	v_mfma_f32_16x16x32_bf16 v[40:43], v[140:143], v[160:163], v[40:43]
	v_mfma_f32_16x16x32_bf16 v[28:31], v[128:131], v[168:171], v[28:31]
	v_mfma_f32_16x16x32_bf16 v[24:27], v[140:143], v[168:171], v[24:27]
	v_mfma_f32_16x16x32_bf16 v[12:15], v[128:131], v[194:197], v[12:15]
	v_mfma_f32_16x16x32_bf16 v[8:11], v[140:143], v[194:197], v[8:11]
	v_mfma_f32_16x16x32_bf16 v[60:63], v[132:135], v[156:159], v[60:63]
	v_mfma_f32_16x16x32_bf16 v[56:59], v[144:147], v[156:159], v[56:59]
	v_mfma_f32_16x16x32_bf16 v[44:47], v[132:135], v[164:167], v[44:47]
	v_mfma_f32_16x16x32_bf16 v[40:43], v[144:147], v[164:167], v[40:43]
	v_mfma_f32_16x16x32_bf16 v[28:31], v[132:135], v[172:175], v[28:31]
	v_mfma_f32_16x16x32_bf16 v[24:27], v[144:147], v[172:175], v[24:27]
	v_mfma_f32_16x16x32_bf16 v[12:15], v[132:135], v[198:201], v[12:15]
	v_mfma_f32_16x16x32_bf16 v[8:11], v[144:147], v[198:201], v[8:11]
	s_setprio 0
	s_barrier
; #define PG8_STAGE(bufoff, gbase, voff) do { _Pragma("unroll") for (int _i = 0; _i < 2; ++_i) { const char* _gb = (const char*)(gbase) + (size_t)_i * (voff##_q); asm volatile("" : "+s"(_gb)); \
;         __builtin_amdgcn_global_load_lds((const unsigned*)(_gb + (voff)), (LAS unsigned*)(lds + (bufoff) + ldsw + _i * 8192), 16, 0, 0); } } while (0)
; #define PG8_LDA(dst, b, h) do { _Pragma("unroll") for (int m = 0; m < 4; ++m) _Pragma("unroll") for (int k = 0; k < 2; ++k) dst[m][k] = *(const LAS bf16x8*)(lds + PG8_SA(b, h) + aoff + m * 2048 + k * 1024); } while (0)
; #define PG8_LDB(dst, b, h) do { _Pragma("unroll") for (int n = 0; n < 2; ++n) _Pragma("unroll") for (int k = 0; k < 2; ++k) dst[n][k] = *(const LAS bf16x8*)(lds + PG8_SB(b, h) + boff + n * 2048 + k * 1024); } while (0)
; #define PG8_MMA(ai, bj, At, Bt) do { __builtin_amdgcn_s_setprio(1); _Pragma("unroll") for (int m = 0; m < 4; ++m) _Pragma("unroll") for (int n = 0; n < 2; ++n) _Pragma("unroll") for (int k = 0; k < 2; ++k) \
;         acc[ai][bj][m][n] = __builtin_amdgcn_mfma_f32_16x16x32_bf16(Bt[n][k], At[m][k], acc[ai][bj][m][n], 0, 0, 0); __builtin_amdgcn_s_setprio(0); } while (0)
; #define PG8_WAIT_V(n) asm volatile("s_waitcnt vmcnt(" #n ")" ::: "memory")
; #define PG8_WAIT_L(n) asm volatile("s_waitcnt lgkmcnt(" #n ")" ::: "memory")
; #define PG8_BAR __builtin_amdgcn_s_barrier()
; #define PG8_SCHED __builtin_amdgcn_sched_barrier(0)
; template <class Epi, class Sched>
; __device__ __forceinline__ void gemm_phase(int wv, LAS unsigned char* lds, const Gemm g, const Sched& S, const Epi& E) { LIDS
;     ...
;             PG8_STAGE(PG8_SB(0, 1), b2 + hstepB, voffB);
;             PG8_WAIT_V(6); PG8_BAR; PG8_MMA(1, 1, At, B1); PG8_BAR;
;             PG8_LDB(B0, 1, 0); PG8_SCHED; PG8_LDA(At, 1, 0); PG8_STAGE(PG8_SA(0, 1), a2 + hstepA, voffA);
;             PG8_WAIT_L(8); PG8_BAR; PG8_WAIT_L(0); PG8_MMA(0, 0, At, B0); PG8_BAR; PG8_SCHED;
;             PG8_LDB(B1, 1, 1); PG8_STAGE(PG8_SB(1, 0), b3, voffB);
;             PG8_BAR; PG8_WAIT_L(0); PG8_MMA(0, 1, At, B1); PG8_BAR;
	s_add_u32 s20, s88, 0x20000
	s_addc_u32 s21, s89, 0
	s_add_i32 s19, s22, s90
	v_lshl_add_u64 v[128:129], s[20:21], 0, v[138:139]
	s_add_u32 s20, s88, 0x30000
	s_mov_b32 m0, s19
	s_addc_u32 s21, s89, 0
	global_load_lds_dwordx4 v[128:129], off
	s_add_i32 m0, s19, 0x2000
	v_lshl_add_u64 v[128:129], s[20:21], 0, v[138:139]
	global_load_lds_dwordx4 v[128:129], off
	s_waitcnt vmcnt(6)
	s_barrier
	s_setprio 1
	v_mfma_f32_16x16x32_bf16 v[52:55], v[202:205], v[152:155], v[52:55]
	v_mfma_f32_16x16x32_bf16 v[48:51], v[218:221], v[152:155], v[48:51]
	v_mfma_f32_16x16x32_bf16 v[36:39], v[202:205], v[160:163], v[36:39]
	v_mfma_f32_16x16x32_bf16 v[32:35], v[218:221], v[160:163], v[32:35]
	v_mfma_f32_16x16x32_bf16 v[20:23], v[202:205], v[168:171], v[20:23]
	v_mfma_f32_16x16x32_bf16 v[16:19], v[218:221], v[168:171], v[16:19]
	v_mfma_f32_16x16x32_bf16 v[4:7], v[202:205], v[194:197], v[4:7]
	v_mfma_f32_16x16x32_bf16 v[0:3], v[218:221], v[194:197], v[0:3]
	v_mfma_f32_16x16x32_bf16 v[52:55], v[206:209], v[156:159], v[52:55]
	v_mfma_f32_16x16x32_bf16 v[48:51], v[222:225], v[156:159], v[48:51]
	v_mfma_f32_16x16x32_bf16 v[36:39], v[206:209], v[164:167], v[36:39]
	v_mfma_f32_16x16x32_bf16 v[32:35], v[222:225], v[164:167], v[32:35]
	v_mfma_f32_16x16x32_bf16 v[20:23], v[206:209], v[172:175], v[20:23]
	v_mfma_f32_16x16x32_bf16 v[16:19], v[222:225], v[172:175], v[16:19]
	v_mfma_f32_16x16x32_bf16 v[4:7], v[206:209], v[198:201], v[4:7]
	v_mfma_f32_16x16x32_bf16 v[0:3], v[222:225], v[198:201], v[0:3]
	s_setprio 0
	s_add_i32 s19, 16, 0x18000
	v_add_u32_e32 v144, s19, v149
	s_barrier
	ds_read_b128 v[128:131], v144
	ds_read_b128 v[132:135], v144 offset:1024
	ds_read_b128 v[140:143], v144 offset:2048
	ds_read_b128 v[144:147], v144 offset:3072
	s_add_u32 s20, s84, 0x100000
	s_addc_u32 s21, s85, 0
	ds_read_b128 v[152:155], v150 offset:32768
	ds_read_b128 v[156:159], v150 offset:33792
	ds_read_b128 v[160:163], v150 offset:34816
	ds_read_b128 v[164:167], v150 offset:35840
	ds_read_b128 v[168:171], v150 offset:36864
	ds_read_b128 v[172:175], v150 offset:37888
	ds_read_b128 v[194:197], v150 offset:38912
	ds_read_b128 v[198:201], v150 offset:39936
	s_mov_b32 m0, s95
	v_lshl_add_u64 v[178:179], s[20:21], 0, v[136:137]
	s_add_u32 s20, s84, 0x180000
	s_addc_u32 s21, s85, 0
	global_load_lds_dwordx4 v[178:179], off
	s_mov_b32 m0, s59
	v_lshl_add_u64 v[178:179], s[20:21], 0, v[136:137]
	global_load_lds_dwordx4 v[178:179], off
	s_waitcnt lgkmcnt(8)
	s_barrier
	s_waitcnt lgkmcnt(0)
	s_setprio 1
	s_waitcnt lgkmcnt(0)
	v_mfma_f32_16x16x32_bf16 v[124:127], v[128:131], v[152:155], v[124:127]
	v_mfma_f32_16x16x32_bf16 v[120:123], v[140:143], v[152:155], v[120:123]
	v_mfma_f32_16x16x32_bf16 v[108:111], v[128:131], v[160:163], v[108:111]
	v_mfma_f32_16x16x32_bf16 v[104:107], v[140:143], v[160:163], v[104:107]
	v_mfma_f32_16x16x32_bf16 v[92:95], v[128:131], v[168:171], v[92:95]
	v_mfma_f32_16x16x32_bf16 v[88:91], v[140:143], v[168:171], v[88:91]
	v_mfma_f32_16x16x32_bf16 v[76:79], v[128:131], v[194:197], v[76:79]
	v_mfma_f32_16x16x32_bf16 v[72:75], v[140:143], v[194:197], v[72:75]
	v_mfma_f32_16x16x32_bf16 v[124:127], v[132:135], v[156:159], v[124:127]
	v_mfma_f32_16x16x32_bf16 v[120:123], v[144:147], v[156:159], v[120:123]
	v_mfma_f32_16x16x32_bf16 v[108:111], v[132:135], v[164:167], v[108:111]
	v_mfma_f32_16x16x32_bf16 v[104:107], v[144:147], v[164:167], v[104:107]
	v_mfma_f32_16x16x32_bf16 v[92:95], v[132:135], v[172:175], v[92:95]
	v_mfma_f32_16x16x32_bf16 v[88:91], v[144:147], v[172:175], v[88:91]
	v_mfma_f32_16x16x32_bf16 v[76:79], v[132:135], v[198:201], v[76:79]
	v_mfma_f32_16x16x32_bf16 v[72:75], v[144:147], v[198:201], v[72:75]
	s_setprio 0
	s_barrier
	s_add_i32 s22, 16, 0x1c000
	v_add_u32_e32 v151, s22, v149
	s_mov_b64 s[20:21], s[78:79]
	ds_read_b128 v[202:205], v151
	ds_read_b128 v[206:209], v151 offset:1024
	ds_read_b128 v[218:221], v151 offset:2048
	ds_read_b128 v[222:225], v151 offset:3072
	s_add_i32 s19, s19, s90
	v_lshl_add_u64 v[178:179], s[20:21], 0, v[138:139]
	s_add_u32 s20, s78, 0x10000
	s_mov_b32 m0, s19
	s_addc_u32 s21, s79, 0
	global_load_lds_dwordx4 v[178:179], off
	s_add_i32 m0, s19, 0x2000
	v_lshl_add_u64 v[178:179], s[20:21], 0, v[138:139]
	global_load_lds_dwordx4 v[178:179], off
	s_barrier
	s_waitcnt lgkmcnt(0)
	s_setprio 1
	s_waitcnt lgkmcnt(0)
	v_mfma_f32_16x16x32_bf16 v[116:119], v[202:205], v[152:155], v[116:119]
	v_mfma_f32_16x16x32_bf16 v[112:115], v[218:221], v[152:155], v[112:115]
	v_mfma_f32_16x16x32_bf16 v[100:103], v[202:205], v[160:163], v[100:103]
	v_mfma_f32_16x16x32_bf16 v[96:99], v[218:221], v[160:163], v[96:99]
	v_mfma_f32_16x16x32_bf16 v[84:87], v[202:205], v[168:171], v[84:87]
	v_mfma_f32_16x16x32_bf16 v[80:83], v[218:221], v[168:171], v[80:83]
	v_mfma_f32_16x16x32_bf16 v[68:71], v[202:205], v[194:197], v[68:71]
	v_mfma_f32_16x16x32_bf16 v[64:67], v[218:221], v[194:197], v[64:67]
	v_mfma_f32_16x16x32_bf16 v[116:119], v[206:209], v[156:159], v[116:119]
	v_mfma_f32_16x16x32_bf16 v[112:115], v[222:225], v[156:159], v[112:115]
	v_mfma_f32_16x16x32_bf16 v[100:103], v[206:209], v[164:167], v[100:103]
	v_mfma_f32_16x16x32_bf16 v[96:99], v[222:225], v[164:167], v[96:99]
	v_mfma_f32_16x16x32_bf16 v[84:87], v[206:209], v[172:175], v[84:87]
	v_mfma_f32_16x16x32_bf16 v[80:83], v[222:225], v[172:175], v[80:83]
	v_mfma_f32_16x16x32_bf16 v[68:71], v[206:209], v[198:201], v[68:71]
	v_mfma_f32_16x16x32_bf16 v[64:67], v[222:225], v[198:201], v[64:67]
	s_setprio 0
	s_mov_b64 s[20:21], s[86:87]
	s_barrier
; #define PG8_STAGE(bufoff, gbase, voff) do { _Pragma("unroll") for (int _i = 0; _i < 2; ++_i) { const char* _gb = (const char*)(gbase) + (size_t)_i * (voff##_q); asm volatile("" : "+s"(_gb)); \
;         __builtin_amdgcn_global_load_lds((const unsigned*)(_gb + (voff)), (LAS unsigned*)(lds + (bufoff) + ldsw + _i * 8192), 16, 0, 0); } } while (0)
; #define PG8_BAR __builtin_amdgcn_s_barrier()
; template <class Epi, class Sched>
; __device__ __forceinline__ void gemm_phase(int wv, LAS unsigned char* lds, const Gemm g, const Sched& S, const Epi& E) { LIDS
;     ...
;             PG8_LDA(At, 1, 1); PG8_STAGE(PG8_SA(1, 0), a3, voffA);
;             PG8_BAR; PG8_WAIT_L(0); PG8_MMA(1, 0, At, B0); PG8_BAR; PG8_SCHED;
;             PG8_STAGE(PG8_SB(1, 1), b3 + hstepB, voffB);
;             PG8_WAIT_V(6); PG8_BAR; PG8_MMA(1, 1, At, B1); PG8_BAR;
;     __device__ __forceinline__ void operator()(const AccT& acc, const Unit& u, int wr, int wc, int fr, int fq) const {
;     ...
; #pragma unroll
;         for (int ai = 0; ai < 2; ++ai)
; #pragma unroll
;             for (int m = 0; m < 4; ++m) {
;                 const int row = row0 + ai * HALF + m * 16;
;                 const f32x4 pa = *(const f32x4*)(ssp + (size_t)row * 16), pb = *(const f32x4*)(ssp + (size_t)row * 16 + 4);
;                 const float ssr = ((pa[0] + pa[1]) + (pa[2] + pa[3])) + ((pb[0] + pb[1]) + (pb[2] + pb[3]));
;                 const float sc = rsqrtf(ssr * (1.0f / 512.0f) + EPS) * (1.4426950408889634f * 0.07216878364870322f);
; #pragma unroll
;                 for (int bj = 0; bj < 2; ++bj) {
;                     const int col = colbase + bj * HALF; f32x4 v0 = acc[ai][bj][m][0], v1 = acc[ai][bj][m][1];
;                     const int d = col % 192;
;                     if (d >= 128) { const int i0 = (d - 128) >> 1;
;                         const f32x4 c4 = *(const f32x4*)(cosT + (size_t)row * 32 + i0), s4 = *(const f32x4*)(sinT + (size_t)row * 32 + i0);
;                         f32x4 o0, o1;
;                         o0[0] = v0[0] * c4[0] - v0[1] * s4[0]; o0[1] = v0[1] * c4[0] + v0[0] * s4[0];
;                         o0[2] = v0[2] * c4[1] - v0[3] * s4[1]; o0[3] = v0[3] * c4[1] + v0[2] * s4[1];
;                         o1[0] = v1[0] * c4[2] - v1[1] * s4[2]; o1[1] = v1[1] * c4[2] + v1[0] * s4[2];
;                         o1[2] = v1[2] * c4[3] - v1[3] * s4[3]; o1[3] = v1[3] * c4[3] + v1[2] * s4[3];
	ds_read_b128 v[152:155], v150 offset:49152
	ds_read_b128 v[156:159], v150 offset:50176
	ds_read_b128 v[160:163], v150 offset:51200
	ds_read_b128 v[164:167], v150 offset:52224
	ds_read_b128 v[168:171], v150 offset:53248
	ds_read_b128 v[172:175], v150 offset:54272
	ds_read_b128 v[194:197], v150 offset:55296
	ds_read_b128 v[198:201], v150 offset:56320
	s_mov_b32 m0, s55
	v_lshl_add_u64 v[178:179], s[20:21], 0, v[136:137]
	s_add_u32 s20, s86, 0x80000
	s_addc_u32 s21, s87, 0
	global_load_lds_dwordx4 v[178:179], off
	s_mov_b32 m0, s57
	v_lshl_add_u64 v[178:179], s[20:21], 0, v[136:137]
	global_load_lds_dwordx4 v[178:179], off
	s_barrier
	s_waitcnt lgkmcnt(0)
	s_setprio 1
	s_waitcnt lgkmcnt(0)
	v_mfma_f32_16x16x32_bf16 v[60:63], v[128:131], v[152:155], v[60:63]
	v_mfma_f32_16x16x32_bf16 v[56:59], v[140:143], v[152:155], v[56:59]
	v_mfma_f32_16x16x32_bf16 v[44:47], v[128:131], v[160:163], v[44:47]
	v_mfma_f32_16x16x32_bf16 v[40:43], v[140:143], v[160:163], v[40:43]
	v_mfma_f32_16x16x32_bf16 v[28:31], v[128:131], v[168:171], v[28:31]
	v_mfma_f32_16x16x32_bf16 v[24:27], v[140:143], v[168:171], v[24:27]
	v_mfma_f32_16x16x32_bf16 v[12:15], v[128:131], v[194:197], v[12:15]
	v_mfma_f32_16x16x32_bf16 v[8:11], v[140:143], v[194:197], v[8:11]
	v_mfma_f32_16x16x32_bf16 v[60:63], v[132:135], v[156:159], v[60:63]
	v_mfma_f32_16x16x32_bf16 v[56:59], v[144:147], v[156:159], v[56:59]
	v_mfma_f32_16x16x32_bf16 v[44:47], v[132:135], v[164:167], v[44:47]
	v_mfma_f32_16x16x32_bf16 v[40:43], v[144:147], v[164:167], v[40:43]
	v_mfma_f32_16x16x32_bf16 v[28:31], v[132:135], v[172:175], v[28:31]
	v_mfma_f32_16x16x32_bf16 v[24:27], v[144:147], v[172:175], v[24:27]
	v_mfma_f32_16x16x32_bf16 v[12:15], v[132:135], v[198:201], v[12:15]
	v_mfma_f32_16x16x32_bf16 v[8:11], v[144:147], v[198:201], v[8:11]
	s_setprio 0
	s_barrier
	s_add_u32 s20, s78, 0x20000
	s_addc_u32 s21, s79, 0
	s_add_i32 s19, s22, s90
	v_lshl_add_u64 v[128:129], s[20:21], 0, v[138:139]
	s_add_u32 s20, s78, 0x30000
	s_mov_b32 m0, s19
	s_addc_u32 s21, s79, 0
	global_load_lds_dwordx4 v[128:129], off
	s_add_i32 m0, s19, 0x2000
	v_lshl_add_u64 v[128:129], s[20:21], 0, v[138:139]
	global_load_lds_dwordx4 v[128:129], off
	s_waitcnt vmcnt(6)
	s_barrier
	s_setprio 1
	v_mfma_f32_16x16x32_bf16 v[52:55], v[202:205], v[152:155], v[52:55]
	v_mfma_f32_16x16x32_bf16 v[48:51], v[218:221], v[152:155], v[48:51]
	v_mfma_f32_16x16x32_bf16 v[36:39], v[202:205], v[160:163], v[36:39]
	v_mfma_f32_16x16x32_bf16 v[32:35], v[218:221], v[160:163], v[32:35]
	v_mfma_f32_16x16x32_bf16 v[20:23], v[202:205], v[168:171], v[20:23]
	v_mfma_f32_16x16x32_bf16 v[16:19], v[218:221], v[168:171], v[16:19]
	v_mfma_f32_16x16x32_bf16 v[4:7], v[202:205], v[194:197], v[4:7]
	v_mfma_f32_16x16x32_bf16 v[0:3], v[218:221], v[194:197], v[0:3]
	v_mfma_f32_16x16x32_bf16 v[52:55], v[206:209], v[156:159], v[52:55]
	v_mfma_f32_16x16x32_bf16 v[48:51], v[222:225], v[156:159], v[48:51]
	v_mfma_f32_16x16x32_bf16 v[36:39], v[206:209], v[164:167], v[36:39]
	v_mfma_f32_16x16x32_bf16 v[32:35], v[222:225], v[164:167], v[32:35]
	v_mfma_f32_16x16x32_bf16 v[20:23], v[206:209], v[172:175], v[20:23]
	v_mfma_f32_16x16x32_bf16 v[16:19], v[222:225], v[172:175], v[16:19]
	v_mfma_f32_16x16x32_bf16 v[4:7], v[206:209], v[198:201], v[4:7]
	v_mfma_f32_16x16x32_bf16 v[0:3], v[222:225], v[198:201], v[0:3]
	s_setprio 0
	s_add_i32 s18, s18, 2
	s_add_u32 s16, s16, 0x100
	s_addc_u32 s17, s17, 0
	s_cmp_gt_u32 s18, 5
	s_barrier
	s_cbranch_scc0 .LBB0_123
	s_lshl_b32 s7, s8, 8
	s_add_i32 s7, s7, s52
	v_mbcnt_lo_u32_b32 v140, -1, 0
	v_mbcnt_hi_u32_b32 v140, -1, v140
	v_readlane_b32 s8, v253, 12
	v_and_or_b32 v142, v140, 15, s7
	v_ashrrev_i32_e32 v143, 31, v142
	v_lshlrev_b64 v[128:129], 6, v[142:143]
	v_readlane_b32 s9, v253, 13
	s_lshl_b32 s6, s6, 8
	v_ashrrev_i32_e32 v140, 1, v140
	v_lshl_add_u64 v[132:133], s[8:9], 0, v[128:129]
	global_load_dword v182, v[132:133], off offset:1024
	global_load_dword v183, v[132:133], off offset:2048
	global_load_dword v184, v[132:133], off offset:3072
	v_add_co_u32_e32 v180, vcc, 0x2000, v132
	s_nop 1
	v_addc_co_u32_e32 v181, vcc, 0, v133, vcc
	global_load_dword v185, v[180:181], off
	global_load_dword v186, v[180:181], off offset:1024
	global_load_dword v187, v[180:181], off offset:2048
	global_load_dword v188, v[180:181], off offset:3072
	global_load_dwordx4 v[128:131], v[132:133], off offset:16
	s_nop 0
	global_load_dwordx4 v[132:135], v[132:133], off
	s_or_b32 s6, s6, s53
	v_and_b32_e32 v140, -8, v140
	v_add_u32_e32 v140, s6, v140
	v_mul_hi_i32 v141, v140, s33
	v_lshlrev_b64 v[144:145], 5, v[142:143]
	v_lshrrev_b32_e32 v143, 31, v141
	v_lshrrev_b32_e32 v141, 5, v141
	v_add_u32_e32 v141, v141, v143
	s_movk_i32 s6, 0xc0
	v_mul_lo_u32 v141, v141, s6
	v_sub_u32_e32 v141, v140, v141
	s_movk_i32 s6, 0x7f
	v_cmp_lt_i32_e32 vcc, s6, v141
	v_readlane_b32 s6, v254, 48
	v_lshlrev_b64 v[144:145], 2, v[144:145]
	v_readlane_b32 s7, v254, 49
	v_add_u32_e32 v141, 0xffffff80, v141
	v_lshrrev_b32_e32 v176, 1, v141
	v_lshl_add_u64 v[146:147], s[6:7], 0, v[144:145]
	v_readlane_b32 s6, v253, 14
	v_readlane_b32 s7, v253, 15
	s_nop 1
	v_lshl_add_u64 v[144:145], s[6:7], 0, v[144:145]
	s_and_saveexec_b64 s[6:7], vcc
	s_cbranch_execz .LBB0_126
	v_lshlrev_b64 v[156:157], 2, v[176:177]
	v_lshl_add_u64 v[152:153], v[146:147], 0, v[156:157]
	v_lshl_add_u64 v[156:157], v[144:145], 0, v[156:157]
	global_load_dwordx4 v[152:155], v[152:153], off
	s_nop 0
	global_load_dwordx4 v[156:159], v[156:157], off
	s_waitcnt vmcnt(0)
	v_pk_mul_f32 v[160:161], v[124:125], v[152:153]
	v_pk_mul_f32 v[162:163], v[124:125], v[156:157] op_sel:[1,0] op_sel_hi:[0,0]
	v_pk_fma_f32 v[124:125], v[124:125], v[152:153], v[162:163] op_sel_hi:[1,0,1]
	v_mov_b32_e32 v156, v153
	v_mul_f32_e32 v124, v127, v157
	v_pk_fma_f32 v[164:165], v[126:127], v[156:157], v[124:125] op_sel_hi:[1,1,0] neg_lo:[0,0,1] neg_hi:[0,0,1]
	v_mov_b32_e32 v152, v157
	v_mul_f32_e32 v124, v127, v153
	v_pk_mul_f32 v[156:157], v[120:121], v[158:159] op_sel:[1,0] op_sel_hi:[0,0]
	v_pk_fma_f32 v[152:153], v[126:127], v[152:153], v[124:125] op_sel_hi:[1,1,0]
	v_pk_mul_f32 v[126:127], v[120:121], v[154:155]
	v_pk_fma_f32 v[120:121], v[120:121], v[154:155], v[156:157] op_sel_hi:[1,0,1]
	v_mov_b32_e32 v158, v155
	v_mul_f32_e32 v120, v123, v159
	v_pk_fma_f32 v[166:167], v[122:123], v[158:159], v[120:121] op_sel_hi:[1,1,0] neg_lo:[0,0,1] neg_hi:[0,0,1]
	v_mov_b32_e32 v154, v159
	v_mul_f32_e32 v120, v123, v155
	v_pk_fma_f32 v[154:155], v[122:123], v[154:155], v[120:121] op_sel_hi:[1,1,0]
	v_sub_f32_e32 v124, v160, v162
	v_sub_f32_e32 v120, v126, v156
	v_mov_b32_e32 v126, v164
	v_mov_b32_e32 v127, v152
	v_mov_b32_e32 v122, v166
	v_mov_b32_e32 v123, v154

; #define PG8_STAGE(bufoff, gbase, voff) do { _Pragma("unroll") for (int _i = 0; _i < 2; ++_i) { const char* _gb = (const char*)(gbase) + (size_t)_i * (voff##_q); asm volatile("" : "+s"(_gb)); \
;         __builtin_amdgcn_global_load_lds((const unsigned*)(_gb + (voff)), (LAS unsigned*)(lds + (bufoff) + ldsw + _i * 8192), 16, 0, 0); } } while (0)
; #define PG8_LDA(dst, b, h) do { _Pragma("unroll") for (int m = 0; m < 4; ++m) _Pragma("unroll") for (int k = 0; k < 2; ++k) dst[m][k] = *(const LAS bf16x8*)(lds + PG8_SA(b, h) + aoff + m * 2048 + k * 1024); } while (0)
; #define PG8_LDB(dst, b, h) do { _Pragma("unroll") for (int n = 0; n < 2; ++n) _Pragma("unroll") for (int k = 0; k < 2; ++k) dst[n][k] = *(const LAS bf16x8*)(lds + PG8_SB(b, h) + boff + n * 2048 + k * 1024); } while (0)
; #define PG8_WAIT_L(n) asm volatile("s_waitcnt lgkmcnt(" #n ")" ::: "memory")
; #define PG8_BAR __builtin_amdgcn_s_barrier()
; #define PG8_SCHED __builtin_amdgcn_sched_barrier(0)
; template <class Epi, class Sched>
; __device__ __forceinline__ void gemm_phase(int wv, LAS unsigned char* lds, const Gemm g, const Sched& S, const Epi& E) { LIDS
;     ...
;         const bool has_next = S.next(ui + 1, nxt);
;         const char* nA = has_next ? (const char*)g.A + (size_t)nxt.pm * g.tstepA : cA; const char* nB = has_next ? (const char*)g.Bt + (size_t)nxt.pn * g.tstepB : cB;
;         for (int t = 0; t < nt; t += 2) {
;             const bool last = (t == nt - 2);
;             const char* a1 = cA + (size_t)(t + 1) * kstepA;
;             const char* a2 = last ? nA : cA + (size_t)(t + 2) * kstepA; const char* b2 = last ? nB : cB + (size_t)(t + 2) * kstepB;
;             const char* a3 = a2 + kstepA; const char* b3 = b2 + kstepB;
;             asm volatile("" : "+s"(a1), "+s"(a2), "+s"(b2), "+s"(a3), "+s"(b3));
;             PG8_LDB(B0, 0, 0); PG8_SCHED; PG8_LDA(At, 0, 0); PG8_STAGE(PG8_SA(1, 1), a1 + hstepA, voffA);
;             PG8_WAIT_L(8); PG8_BAR; PG8_WAIT_L(0); PG8_MMA(0, 0, At, B0); PG8_BAR; PG8_SCHED;
;             PG8_LDB(B1, 0, 1); PG8_STAGE(PG8_SB(0, 0), b2, voffB);
;             PG8_BAR; PG8_WAIT_L(0); PG8_MMA(0, 1, At, B1); PG8_BAR;
;             PG8_LDA(At, 0, 1); PG8_STAGE(PG8_SA(0, 0), a2, voffA);
;             PG8_BAR; PG8_WAIT_L(0); PG8_MMA(1, 0, At, B0); PG8_BAR; PG8_SCHED;
.LBB0_168:
	s_ashr_i32 s11, s10, 31
	s_lshl_b64 s[12:13], s[10:11], 21
	v_readlane_b32 s9, v253, 16
	v_mov_b64_e32 v[4:5], 0x100
	s_add_u32 s12, s9, s12
	v_readlane_b32 s9, v253, 17
	v_cmp_lt_i64_e32 vcc, s[6:7], v[4:5]
	s_addc_u32 s13, s9, s13
	s_and_b64 s[18:19], vcc, exec
	s_cselect_b32 s73, s13, s87
	s_cselect_b32 s72, s12, s86
	s_ashr_i32 s9, s8, 31
	s_lshl_b64 s[18:19], s[8:9], 17
	v_readlane_b32 s20, v253, 18
	v_readlane_b32 s21, v253, 19
	s_add_u32 s62, s20, s18
	s_addc_u32 s63, s21, s19
	s_and_b64 s[18:19], vcc, exec
	s_cselect_b32 s79, s63, s91
	s_cselect_b32 s78, s62, s90
	s_add_u32 s18, s86, 0x80
	s_addc_u32 s19, s87, 0
	s_add_u32 s88, s86, 0x100
	s_addc_u32 s89, s87, 0
	s_add_u32 s94, s90, 0x100
	s_addc_u32 s95, s91, 0
	s_add_u32 s86, s86, 0x180
	s_addc_u32 s87, s87, 0
	s_add_u32 s90, s90, 0x180
	s_addc_u32 s91, s91, 0
	s_add_i32 s11, 16, 0x10000
	s_mov_b64 s[84:85], s[86:87]
	v_add_u32_e32 v176, s11, v134
	ds_read_b128 v[4:7], v176
	ds_read_b128 v[8:11], v176 offset:1024
	ds_read_b128 v[12:15], v176 offset:2048
	ds_read_b128 v[16:19], v176 offset:3072
	s_add_u32 s20, s18, 0x100000
	s_addc_u32 s21, s19, 0
	s_add_i32 s22, s58, 0xc000
	s_add_u32 s18, s18, 0x180000
	ds_read_b128 v[20:23], v135
	ds_read_b128 v[24:27], v135 offset:1024
	ds_read_b128 v[28:31], v135 offset:2048
	ds_read_b128 v[32:35], v135 offset:3072
	ds_read_b128 v[36:39], v135 offset:4096
	ds_read_b128 v[40:43], v135 offset:5120
	ds_read_b128 v[44:47], v135 offset:6144
	ds_read_b128 v[48:51], v135 offset:7168
	s_mov_b32 m0, s22
	v_lshl_add_u64 v[52:53], s[20:21], 0, v[124:125]
	s_addc_u32 s19, s19, 0
	s_add_i32 s9, s58, 0xe000
	global_load_lds_dwordx4 v[52:53], off
	s_mov_b32 m0, s9
	v_lshl_add_u64 v[52:53], s[18:19], 0, v[124:125]
	global_load_lds_dwordx4 v[52:53], off
	s_waitcnt lgkmcnt(8)
	s_barrier
	s_waitcnt lgkmcnt(0)
	s_setprio 1
	s_waitcnt lgkmcnt(0)
	v_mfma_f32_16x16x32_bf16 v[52:55], v[4:7], v[20:23], v[0:3]
	v_mfma_f32_16x16x32_bf16 v[56:59], v[12:15], v[20:23], v[0:3]
	v_mfma_f32_16x16x32_bf16 v[60:63], v[4:7], v[28:31], v[0:3]
	v_mfma_f32_16x16x32_bf16 v[64:67], v[12:15], v[28:31], v[0:3]
	v_mfma_f32_16x16x32_bf16 v[68:71], v[4:7], v[36:39], v[0:3]
	v_mfma_f32_16x16x32_bf16 v[72:75], v[12:15], v[36:39], v[0:3]
	v_mfma_f32_16x16x32_bf16 v[76:79], v[4:7], v[44:47], v[0:3]
	v_mfma_f32_16x16x32_bf16 v[80:83], v[12:15], v[44:47], v[0:3]
	v_mfma_f32_16x16x32_bf16 v[52:55], v[8:11], v[24:27], v[52:55]
	v_mfma_f32_16x16x32_bf16 v[56:59], v[16:19], v[24:27], v[56:59]
	v_mfma_f32_16x16x32_bf16 v[60:63], v[8:11], v[32:35], v[60:63]
	v_mfma_f32_16x16x32_bf16 v[64:67], v[16:19], v[32:35], v[64:67]
	v_mfma_f32_16x16x32_bf16 v[68:71], v[8:11], v[40:43], v[68:71]
	v_mfma_f32_16x16x32_bf16 v[72:75], v[16:19], v[40:43], v[72:75]
	v_mfma_f32_16x16x32_bf16 v[76:79], v[8:11], v[48:51], v[76:79]
	v_mfma_f32_16x16x32_bf16 v[80:83], v[16:19], v[48:51], v[80:83]
	s_setprio 0
	s_barrier
	s_add_i32 s21, 16, 0x14000
	v_add_u32_e32 v178, s21, v134
	s_mov_b64 s[18:19], s[94:95]
	ds_read_b128 v[84:87], v178
	ds_read_b128 v[88:91], v178 offset:1024
	ds_read_b128 v[92:95], v178 offset:2048
	ds_read_b128 v[96:99], v178 offset:3072
	s_add_i32 s20, s11, s57
	v_lshl_add_u64 v[100:101], s[18:19], 0, v[126:127]
	s_add_u32 s18, s94, 0x8000
	s_mov_b32 m0, s20
	s_addc_u32 s19, s95, 0
	s_add_i32 s11, s20, 0x2000
	global_load_lds_dwordx4 v[100:101], off
	s_mov_b32 m0, s11
	v_lshl_add_u64 v[100:101], s[18:19], 0, v[126:127]
	global_load_lds_dwordx4 v[100:101], off
	s_barrier
	s_waitcnt lgkmcnt(0)
	s_setprio 1
	s_waitcnt lgkmcnt(0)
	v_mfma_f32_16x16x32_bf16 v[100:103], v[84:87], v[20:23], v[0:3]
	v_mfma_f32_16x16x32_bf16 v[20:23], v[92:95], v[20:23], v[0:3]
	v_mfma_f32_16x16x32_bf16 v[100:103], v[88:91], v[24:27], v[100:103]
	v_mfma_f32_16x16x32_bf16 v[20:23], v[96:99], v[24:27], v[20:23]
	v_mfma_f32_16x16x32_bf16 v[24:27], v[84:87], v[28:31], v[0:3]
	v_mfma_f32_16x16x32_bf16 v[28:31], v[92:95], v[28:31], v[0:3]
	v_mfma_f32_16x16x32_bf16 v[24:27], v[88:91], v[32:35], v[24:27]
	v_mfma_f32_16x16x32_bf16 v[28:31], v[96:99], v[32:35], v[28:31]
	v_mfma_f32_16x16x32_bf16 v[32:35], v[84:87], v[36:39], v[0:3]
	v_mfma_f32_16x16x32_bf16 v[36:39], v[92:95], v[36:39], v[0:3]
	v_mfma_f32_16x16x32_bf16 v[32:35], v[88:91], v[40:43], v[32:35]
	v_mfma_f32_16x16x32_bf16 v[36:39], v[96:99], v[40:43], v[36:39]
	v_mfma_f32_16x16x32_bf16 v[40:43], v[84:87], v[44:47], v[0:3]
	v_mfma_f32_16x16x32_bf16 v[44:47], v[92:95], v[44:47], v[0:3]
	v_mfma_f32_16x16x32_bf16 v[40:43], v[88:91], v[48:51], v[40:43]
	v_mfma_f32_16x16x32_bf16 v[44:47], v[96:99], v[48:51], v[44:47]
	s_setprio 0
	s_mov_b64 s[18:19], s[88:89]
	s_barrier
	ds_read_b128 v[48:51], v135 offset:16384
	ds_read_b128 v[104:107], v135 offset:17408
	ds_read_b128 v[108:111], v135 offset:18432
	ds_read_b128 v[112:115], v135 offset:19456
	ds_read_b128 v[116:119], v135 offset:20480
	ds_read_b128 v[120:123], v135 offset:21504
	ds_read_b128 v[128:131], v135 offset:22528
	ds_read_b128 v[136:139], v135 offset:23552
	s_mov_b32 m0, s58
	v_lshl_add_u64 v[132:133], s[18:19], 0, v[124:125]
	s_add_u32 s18, s88, 0x80000
	s_addc_u32 s19, s89, 0
	global_load_lds_dwordx4 v[132:133], off
	s_mov_b32 m0, s77
	v_lshl_add_u64 v[132:133], s[18:19], 0, v[124:125]
	global_load_lds_dwordx4 v[132:133], off
	s_barrier
; #define PG8_STAGE(bufoff, gbase, voff) do { _Pragma("unroll") for (int _i = 0; _i < 2; ++_i) { const char* _gb = (const char*)(gbase) + (size_t)_i * (voff##_q); asm volatile("" : "+s"(_gb)); \
;         __builtin_amdgcn_global_load_lds((const unsigned*)(_gb + (voff)), (LAS unsigned*)(lds + (bufoff) + ldsw + _i * 8192), 16, 0, 0); } } while (0)
; #define PG8_LDA(dst, b, h) do { _Pragma("unroll") for (int m = 0; m < 4; ++m) _Pragma("unroll") for (int k = 0; k < 2; ++k) dst[m][k] = *(const LAS bf16x8*)(lds + PG8_SA(b, h) + aoff + m * 2048 + k * 1024); } while (0)
; #define PG8_LDB(dst, b, h) do { _Pragma("unroll") for (int n = 0; n < 2; ++n) _Pragma("unroll") for (int k = 0; k < 2; ++k) dst[n][k] = *(const LAS bf16x8*)(lds + PG8_SB(b, h) + boff + n * 2048 + k * 1024); } while (0)
; #define PG8_MMA(ai, bj, At, Bt) do { __builtin_amdgcn_s_setprio(1); _Pragma("unroll") for (int m = 0; m < 4; ++m) _Pragma("unroll") for (int n = 0; n < 2; ++n) _Pragma("unroll") for (int k = 0; k < 2; ++k) \
;         acc[ai][bj][m][n] = __builtin_amdgcn_mfma_f32_16x16x32_bf16(Bt[n][k], At[m][k], acc[ai][bj][m][n], 0, 0, 0); __builtin_amdgcn_s_setprio(0); } while (0)
; #define PG8_WAIT_V(n) asm volatile("s_waitcnt vmcnt(" #n ")" ::: "memory")
; #define PG8_WAIT_L(n) asm volatile("s_waitcnt lgkmcnt(" #n ")" ::: "memory")
; #define PG8_BAR __builtin_amdgcn_s_barrier()
; #define PG8_SCHED __builtin_amdgcn_sched_barrier(0)
; template <class Epi, class Sched>
; __device__ __forceinline__ void gemm_phase(int wv, LAS unsigned char* lds, const Gemm g, const Sched& S, const Epi& E) { LIDS
;     ...
;             PG8_BAR; PG8_WAIT_L(0); PG8_MMA(1, 0, At, B0); PG8_BAR; PG8_SCHED;
;             PG8_STAGE(PG8_SB(0, 1), b2 + hstepB, voffB);
;             PG8_WAIT_V(6); PG8_BAR; PG8_MMA(1, 1, At, B1); PG8_BAR;
;             PG8_LDB(B0, 1, 0); PG8_SCHED; PG8_LDA(At, 1, 0); PG8_STAGE(PG8_SA(0, 1), a2 + hstepA, voffA);
;             PG8_WAIT_L(8); PG8_BAR; PG8_WAIT_L(0); PG8_MMA(0, 0, At, B0); PG8_BAR; PG8_SCHED;
;             PG8_LDB(B1, 1, 1); PG8_STAGE(PG8_SB(1, 0), b3, voffB);
;             PG8_BAR; PG8_WAIT_L(0); PG8_MMA(0, 1, At, B1); PG8_BAR;
	s_waitcnt lgkmcnt(0)
	s_setprio 1
	s_waitcnt lgkmcnt(0)
	v_mfma_f32_16x16x32_bf16 v[140:143], v[4:7], v[48:51], v[0:3]
	v_mfma_f32_16x16x32_bf16 v[148:151], v[4:7], v[108:111], v[0:3]
	v_mfma_f32_16x16x32_bf16 v[156:159], v[4:7], v[116:119], v[0:3]
	v_mfma_f32_16x16x32_bf16 v[4:7], v[4:7], v[128:131], v[0:3]
	v_mfma_f32_16x16x32_bf16 v[140:143], v[8:11], v[104:107], v[140:143]
	v_mfma_f32_16x16x32_bf16 v[144:147], v[12:15], v[48:51], v[0:3]
	v_mfma_f32_16x16x32_bf16 v[148:151], v[8:11], v[112:115], v[148:151]
	v_mfma_f32_16x16x32_bf16 v[152:155], v[12:15], v[108:111], v[0:3]
	v_mfma_f32_16x16x32_bf16 v[156:159], v[8:11], v[120:123], v[156:159]
	v_mfma_f32_16x16x32_bf16 v[160:163], v[12:15], v[116:119], v[0:3]
	v_mfma_f32_16x16x32_bf16 v[4:7], v[8:11], v[136:139], v[4:7]
	v_mfma_f32_16x16x32_bf16 v[8:11], v[12:15], v[128:131], v[0:3]
	v_mfma_f32_16x16x32_bf16 v[144:147], v[16:19], v[104:107], v[144:147]
	v_mfma_f32_16x16x32_bf16 v[152:155], v[16:19], v[112:115], v[152:155]
	v_mfma_f32_16x16x32_bf16 v[160:163], v[16:19], v[120:123], v[160:163]
	v_mfma_f32_16x16x32_bf16 v[8:11], v[16:19], v[136:139], v[8:11]
	s_setprio 0
	s_barrier
	s_add_u32 s18, s94, 0x10000
	s_addc_u32 s19, s95, 0
	s_add_i32 s21, s21, s57
	v_lshl_add_u64 v[12:13], s[18:19], 0, v[126:127]
	s_add_u32 s18, s94, 0x18000
	s_mov_b32 m0, s21
	s_addc_u32 s19, s95, 0
	s_add_i32 s17, s21, 0x2000
	global_load_lds_dwordx4 v[12:13], off
	s_mov_b32 m0, s17
	v_lshl_add_u64 v[12:13], s[18:19], 0, v[126:127]
	global_load_lds_dwordx4 v[12:13], off
	s_waitcnt vmcnt(6)
	s_barrier
	s_setprio 1
	v_mfma_f32_16x16x32_bf16 v[12:15], v[84:87], v[48:51], v[0:3]
	v_mfma_f32_16x16x32_bf16 v[16:19], v[92:95], v[48:51], v[0:3]
	v_mfma_f32_16x16x32_bf16 v[12:15], v[88:91], v[104:107], v[12:15]
	v_mfma_f32_16x16x32_bf16 v[16:19], v[96:99], v[104:107], v[16:19]
	v_mfma_f32_16x16x32_bf16 v[48:51], v[84:87], v[108:111], v[0:3]
	v_mfma_f32_16x16x32_bf16 v[104:107], v[92:95], v[108:111], v[0:3]
	v_mfma_f32_16x16x32_bf16 v[108:111], v[84:87], v[116:119], v[0:3]
	v_mfma_f32_16x16x32_bf16 v[84:87], v[84:87], v[128:131], v[0:3]
	v_mfma_f32_16x16x32_bf16 v[48:51], v[88:91], v[112:115], v[48:51]
	v_mfma_f32_16x16x32_bf16 v[104:107], v[96:99], v[112:115], v[104:107]
	v_mfma_f32_16x16x32_bf16 v[108:111], v[88:91], v[120:123], v[108:111]
	v_mfma_f32_16x16x32_bf16 v[112:115], v[92:95], v[116:119], v[0:3]
	v_mfma_f32_16x16x32_bf16 v[84:87], v[88:91], v[136:139], v[84:87]
	v_mfma_f32_16x16x32_bf16 v[88:91], v[92:95], v[128:131], v[0:3]
	v_mfma_f32_16x16x32_bf16 v[112:115], v[96:99], v[120:123], v[112:115]
	v_mfma_f32_16x16x32_bf16 v[88:91], v[96:99], v[136:139], v[88:91]
	s_setprio 0
	s_add_i32 s23, 16, 0x18000
	v_add_u32_e32 v179, s23, v134
	s_barrier
	ds_read_b128 v[92:95], v179
	ds_read_b128 v[96:99], v179 offset:1024
	ds_read_b128 v[116:119], v179 offset:2048
	ds_read_b128 v[120:123], v179 offset:3072
	s_add_u32 s18, s88, 0x100000
	s_addc_u32 s19, s89, 0
	ds_read_b128 v[128:131], v135 offset:32768
	ds_read_b128 v[136:139], v135 offset:33792
	ds_read_b128 v[164:167], v135 offset:34816
	ds_read_b128 v[168:171], v135 offset:35840
	ds_read_b128 v[172:175], v135 offset:36864
	ds_read_b128 v[194:197], v135 offset:37888
	ds_read_b128 v[198:201], v135 offset:38912
	ds_read_b128 v[202:205], v135 offset:39936
	s_mov_b32 m0, s82
	v_lshl_add_u64 v[132:133], s[18:19], 0, v[124:125]
	s_add_u32 s18, s88, 0x180000
	s_addc_u32 s19, s89, 0
	global_load_lds_dwordx4 v[132:133], off
	s_mov_b32 m0, s56
	v_lshl_add_u64 v[132:133], s[18:19], 0, v[124:125]
	global_load_lds_dwordx4 v[132:133], off
	s_waitcnt lgkmcnt(8)
	s_barrier
	s_waitcnt lgkmcnt(0)
	s_setprio 1
	s_waitcnt lgkmcnt(0)
	v_mfma_f32_16x16x32_bf16 v[52:55], v[92:95], v[128:131], v[52:55]
	v_mfma_f32_16x16x32_bf16 v[56:59], v[116:119], v[128:131], v[56:59]
	v_mfma_f32_16x16x32_bf16 v[60:63], v[92:95], v[164:167], v[60:63]
	v_mfma_f32_16x16x32_bf16 v[64:67], v[116:119], v[164:167], v[64:67]
	v_mfma_f32_16x16x32_bf16 v[68:71], v[92:95], v[172:175], v[68:71]
	v_mfma_f32_16x16x32_bf16 v[72:75], v[116:119], v[172:175], v[72:75]
	v_mfma_f32_16x16x32_bf16 v[76:79], v[92:95], v[198:201], v[76:79]
	v_mfma_f32_16x16x32_bf16 v[80:83], v[116:119], v[198:201], v[80:83]
	v_mfma_f32_16x16x32_bf16 v[52:55], v[96:99], v[136:139], v[52:55]
	v_mfma_f32_16x16x32_bf16 v[56:59], v[120:123], v[136:139], v[56:59]
	v_mfma_f32_16x16x32_bf16 v[60:63], v[96:99], v[168:171], v[60:63]
	v_mfma_f32_16x16x32_bf16 v[64:67], v[120:123], v[168:171], v[64:67]
	v_mfma_f32_16x16x32_bf16 v[68:71], v[96:99], v[194:197], v[68:71]
	v_mfma_f32_16x16x32_bf16 v[72:75], v[120:123], v[194:197], v[72:75]
	v_mfma_f32_16x16x32_bf16 v[76:79], v[96:99], v[202:205], v[76:79]
	v_mfma_f32_16x16x32_bf16 v[80:83], v[120:123], v[202:205], v[80:83]
	s_setprio 0
	s_barrier
	s_add_i32 s26, 16, 0x1c000
	v_add_u32_e32 v190, s26, v134
	s_mov_b64 s[18:19], s[90:91]
	ds_read_b128 v[206:209], v190
	ds_read_b128 v[218:221], v190 offset:1024
	ds_read_b128 v[222:225], v190 offset:2048
	ds_read_b128 v[226:229], v190 offset:3072
	s_add_i32 s23, s23, s57
	v_lshl_add_u64 v[132:133], s[18:19], 0, v[126:127]
	s_add_u32 s18, s90, 0x8000
	s_mov_b32 m0, s23
	s_addc_u32 s19, s91, 0
	global_load_lds_dwordx4 v[132:133], off
	s_nop 0
	v_lshl_add_u64 v[132:133], s[18:19], 0, v[126:127]
	s_add_i32 s18, s23, 0x2000
	s_mov_b32 m0, s18
	s_nop 0
	global_load_lds_dwordx4 v[132:133], off
	s_barrier
; #define PG8_STAGE(bufoff, gbase, voff) do { _Pragma("unroll") for (int _i = 0; _i < 2; ++_i) { const char* _gb = (const char*)(gbase) + (size_t)_i * (voff##_q); asm volatile("" : "+s"(_gb)); \
;         __builtin_amdgcn_global_load_lds((const unsigned*)(_gb + (voff)), (LAS unsigned*)(lds + (bufoff) + ldsw + _i * 8192), 16, 0, 0); } } while (0)
; #define PG8_LDA(dst, b, h) do { _Pragma("unroll") for (int m = 0; m < 4; ++m) _Pragma("unroll") for (int k = 0; k < 2; ++k) dst[m][k] = *(const LAS bf16x8*)(lds + PG8_SA(b, h) + aoff + m * 2048 + k * 1024); } while (0)
; #define PG8_LDB(dst, b, h) do { _Pragma("unroll") for (int n = 0; n < 2; ++n) _Pragma("unroll") for (int k = 0; k < 2; ++k) dst[n][k] = *(const LAS bf16x8*)(lds + PG8_SB(b, h) + boff + n * 2048 + k * 1024); } while (0)
; #define PG8_MMA(ai, bj, At, Bt) do { __builtin_amdgcn_s_setprio(1); _Pragma("unroll") for (int m = 0; m < 4; ++m) _Pragma("unroll") for (int n = 0; n < 2; ++n) _Pragma("unroll") for (int k = 0; k < 2; ++k) \
;         acc[ai][bj][m][n] = __builtin_amdgcn_mfma_f32_16x16x32_bf16(Bt[n][k], At[m][k], acc[ai][bj][m][n], 0, 0, 0); __builtin_amdgcn_s_setprio(0); } while (0)
; #define PG8_WAIT_V(n) asm volatile("s_waitcnt vmcnt(" #n ")" ::: "memory")
; template <class Epi, class Sched>
; __device__ __forceinline__ void gemm_phase(int wv, LAS unsigned char* lds, const Gemm g, const Sched& S, const Epi& E) { LIDS
;     ...
;             PG8_LDB(B0, 0, 0); PG8_SCHED; PG8_LDA(At, 0, 0); PG8_STAGE(PG8_SA(1, 1), a1 + hstepA, voffA);
;             PG8_WAIT_L(8); PG8_BAR; PG8_WAIT_L(0); PG8_MMA(0, 0, At, B0); PG8_BAR; PG8_SCHED;
;             PG8_LDB(B1, 0, 1); PG8_STAGE(PG8_SB(0, 0), b2, voffB);
;     ...
;             PG8_WAIT_V(6); PG8_BAR; PG8_MMA(1, 1, At, B1); PG8_BAR;
;             PG8_LDB(B0, 1, 0); PG8_SCHED; PG8_LDA(At, 1, 0); PG8_STAGE(PG8_SA(0, 1), a2 + hstepA, voffA);
;             PG8_WAIT_L(8); PG8_BAR; PG8_WAIT_L(0); PG8_MMA(0, 0, At, B0); PG8_BAR; PG8_SCHED;
;             PG8_LDB(B1, 1, 1); PG8_STAGE(PG8_SB(1, 0), b3, voffB);
;             PG8_BAR; PG8_WAIT_L(0); PG8_MMA(0, 1, At, B1); PG8_BAR;
;             PG8_LDA(At, 1, 1); PG8_STAGE(PG8_SA(1, 0), a3, voffA);
;             PG8_BAR; PG8_WAIT_L(0); PG8_MMA(1, 0, At, B0); PG8_BAR; PG8_SCHED;
;             PG8_STAGE(PG8_SB(1, 1), b3 + hstepB, voffB);
;             PG8_WAIT_V(6); PG8_BAR; PG8_MMA(1, 1, At, B1); PG8_BAR;
	s_waitcnt lgkmcnt(0)
	s_setprio 1
	s_waitcnt lgkmcnt(0)
	v_mfma_f32_16x16x32_bf16 v[100:103], v[206:209], v[128:131], v[100:103]
	v_mfma_f32_16x16x32_bf16 v[20:23], v[222:225], v[128:131], v[20:23]
	v_mfma_f32_16x16x32_bf16 v[24:27], v[206:209], v[164:167], v[24:27]
	v_mfma_f32_16x16x32_bf16 v[28:31], v[222:225], v[164:167], v[28:31]
	v_mfma_f32_16x16x32_bf16 v[32:35], v[206:209], v[172:175], v[32:35]
	v_mfma_f32_16x16x32_bf16 v[36:39], v[222:225], v[172:175], v[36:39]
	v_mfma_f32_16x16x32_bf16 v[40:43], v[206:209], v[198:201], v[40:43]
	v_mfma_f32_16x16x32_bf16 v[44:47], v[222:225], v[198:201], v[44:47]
	v_mfma_f32_16x16x32_bf16 v[100:103], v[218:221], v[136:139], v[100:103]
	v_mfma_f32_16x16x32_bf16 v[20:23], v[226:229], v[136:139], v[20:23]
	v_mfma_f32_16x16x32_bf16 v[24:27], v[218:221], v[168:171], v[24:27]
	v_mfma_f32_16x16x32_bf16 v[28:31], v[226:229], v[168:171], v[28:31]
	v_mfma_f32_16x16x32_bf16 v[32:35], v[218:221], v[194:197], v[32:35]
	v_mfma_f32_16x16x32_bf16 v[36:39], v[226:229], v[194:197], v[36:39]
	v_mfma_f32_16x16x32_bf16 v[40:43], v[218:221], v[202:205], v[40:43]
	v_mfma_f32_16x16x32_bf16 v[44:47], v[226:229], v[202:205], v[44:47]
	s_setprio 0
	s_mov_b64 s[24:25], s[84:85]
	s_barrier
	ds_read_b128 v[128:131], v135 offset:49152
	ds_read_b128 v[136:139], v135 offset:50176
	ds_read_b128 v[164:167], v135 offset:51200
	ds_read_b128 v[168:171], v135 offset:52224
	ds_read_b128 v[172:175], v135 offset:53248
	ds_read_b128 v[194:197], v135 offset:54272
	ds_read_b128 v[198:201], v135 offset:55296
	ds_read_b128 v[202:205], v135 offset:56320
	s_mov_b32 m0, s0
	v_lshl_add_u64 v[132:133], s[24:25], 0, v[124:125]
	s_add_u32 s24, s84, 0x80000
	s_addc_u32 s25, s85, 0
	global_load_lds_dwordx4 v[132:133], off
	s_mov_b32 m0, s59
	v_lshl_add_u64 v[132:133], s[24:25], 0, v[124:125]
	global_load_lds_dwordx4 v[132:133], off
	s_barrier
	s_waitcnt lgkmcnt(0)
	s_setprio 1
	s_waitcnt lgkmcnt(0)
	v_mfma_f32_16x16x32_bf16 v[140:143], v[92:95], v[128:131], v[140:143]
	v_mfma_f32_16x16x32_bf16 v[144:147], v[116:119], v[128:131], v[144:147]
	v_mfma_f32_16x16x32_bf16 v[148:151], v[92:95], v[164:167], v[148:151]
	v_mfma_f32_16x16x32_bf16 v[152:155], v[116:119], v[164:167], v[152:155]
	v_mfma_f32_16x16x32_bf16 v[156:159], v[92:95], v[172:175], v[156:159]
	v_mfma_f32_16x16x32_bf16 v[160:163], v[116:119], v[172:175], v[160:163]
	v_mfma_f32_16x16x32_bf16 v[4:7], v[92:95], v[198:201], v[4:7]
	v_mfma_f32_16x16x32_bf16 v[8:11], v[116:119], v[198:201], v[8:11]
	v_mfma_f32_16x16x32_bf16 v[140:143], v[96:99], v[136:139], v[140:143]
	v_mfma_f32_16x16x32_bf16 v[144:147], v[120:123], v[136:139], v[144:147]
	v_mfma_f32_16x16x32_bf16 v[148:151], v[96:99], v[168:171], v[148:151]
	v_mfma_f32_16x16x32_bf16 v[152:155], v[120:123], v[168:171], v[152:155]
	v_mfma_f32_16x16x32_bf16 v[156:159], v[96:99], v[194:197], v[156:159]
	v_mfma_f32_16x16x32_bf16 v[160:163], v[120:123], v[194:197], v[160:163]
	v_mfma_f32_16x16x32_bf16 v[4:7], v[96:99], v[202:205], v[4:7]
	v_mfma_f32_16x16x32_bf16 v[8:11], v[120:123], v[202:205], v[8:11]
	s_setprio 0
	s_barrier
	s_add_u32 s24, s90, 0x10000
	s_addc_u32 s25, s91, 0
	s_nop 0
	v_lshl_add_u64 v[92:93], s[24:25], 0, v[126:127]
	s_add_i32 s24, s26, s57
	s_add_u32 s26, s90, 0x18000
	s_mov_b32 m0, s24
	s_addc_u32 s27, s91, 0
	s_add_i32 s19, s24, 0x2000
	global_load_lds_dwordx4 v[92:93], off
	s_mov_b32 m0, s19
	v_lshl_add_u64 v[92:93], s[26:27], 0, v[126:127]
	global_load_lds_dwordx4 v[92:93], off
	s_waitcnt vmcnt(6)
	s_barrier
	s_setprio 1
	v_mfma_f32_16x16x32_bf16 v[12:15], v[206:209], v[128:131], v[12:15]
	v_mfma_f32_16x16x32_bf16 v[16:19], v[222:225], v[128:131], v[16:19]
	v_mfma_f32_16x16x32_bf16 v[48:51], v[206:209], v[164:167], v[48:51]
	v_mfma_f32_16x16x32_bf16 v[92:95], v[222:225], v[164:167], v[104:107]
	v_mfma_f32_16x16x32_bf16 v[96:99], v[206:209], v[172:175], v[108:111]
	v_mfma_f32_16x16x32_bf16 v[104:107], v[222:225], v[172:175], v[112:115]
	v_mfma_f32_16x16x32_bf16 v[84:87], v[206:209], v[198:201], v[84:87]
	v_mfma_f32_16x16x32_bf16 v[88:91], v[222:225], v[198:201], v[88:91]
	v_mfma_f32_16x16x32_bf16 v[12:15], v[218:221], v[136:139], v[12:15]
	v_mfma_f32_16x16x32_bf16 v[16:19], v[226:229], v[136:139], v[16:19]
	v_mfma_f32_16x16x32_bf16 v[48:51], v[218:221], v[168:171], v[48:51]
	v_mfma_f32_16x16x32_bf16 v[92:95], v[226:229], v[168:171], v[92:95]
	v_mfma_f32_16x16x32_bf16 v[96:99], v[218:221], v[194:197], v[96:99]
	v_mfma_f32_16x16x32_bf16 v[104:107], v[226:229], v[194:197], v[104:107]
	v_mfma_f32_16x16x32_bf16 v[84:87], v[218:221], v[202:205], v[84:87]
	v_mfma_f32_16x16x32_bf16 v[88:91], v[226:229], v[202:205], v[88:91]
	s_setprio 0
	s_add_u32 s84, s72, 0x80
	s_addc_u32 s85, s73, 0
	s_add_u32 s90, s78, 0x80
	s_addc_u32 s91, s79, 0
	s_barrier
	ds_read_b128 v[108:111], v176
	ds_read_b128 v[112:115], v176 offset:1024
	ds_read_b128 v[116:119], v176 offset:2048
	ds_read_b128 v[120:123], v176 offset:3072
	s_add_u32 s26, s86, 0x100000
	s_addc_u32 s27, s87, 0
	ds_read_b128 v[128:131], v135
	ds_read_b128 v[136:139], v135 offset:1024
	ds_read_b128 v[164:167], v135 offset:2048
	ds_read_b128 v[168:171], v135 offset:3072
	ds_read_b128 v[172:175], v135 offset:4096
	ds_read_b128 v[194:197], v135 offset:5120
	ds_read_b128 v[198:201], v135 offset:6144
	ds_read_b128 v[202:205], v135 offset:7168
	s_mov_b32 m0, s22
	v_lshl_add_u64 v[132:133], s[26:27], 0, v[124:125]
	s_add_u32 s26, s86, 0x180000
	s_addc_u32 s27, s87, 0
	global_load_lds_dwordx4 v[132:133], off
	s_mov_b32 m0, s9
	v_lshl_add_u64 v[132:133], s[26:27], 0, v[124:125]
	global_load_lds_dwordx4 v[132:133], off
	s_waitcnt lgkmcnt(8)
	s_barrier
; #define PG8_STAGE(bufoff, gbase, voff) do { _Pragma("unroll") for (int _i = 0; _i < 2; ++_i) { const char* _gb = (const char*)(gbase) + (size_t)_i * (voff##_q); asm volatile("" : "+s"(_gb)); \
;         __builtin_amdgcn_global_load_lds((const unsigned*)(_gb + (voff)), (LAS unsigned*)(lds + (bufoff) + ldsw + _i * 8192), 16, 0, 0); } } while (0)
; #define PG8_LDA(dst, b, h) do { _Pragma("unroll") for (int m = 0; m < 4; ++m) _Pragma("unroll") for (int k = 0; k < 2; ++k) dst[m][k] = *(const LAS bf16x8*)(lds + PG8_SA(b, h) + aoff + m * 2048 + k * 1024); } while (0)
; #define PG8_LDB(dst, b, h) do { _Pragma("unroll") for (int n = 0; n < 2; ++n) _Pragma("unroll") for (int k = 0; k < 2; ++k) dst[n][k] = *(const LAS bf16x8*)(lds + PG8_SB(b, h) + boff + n * 2048 + k * 1024); } while (0)
; #define PG8_MMA(ai, bj, At, Bt) do { __builtin_amdgcn_s_setprio(1); _Pragma("unroll") for (int m = 0; m < 4; ++m) _Pragma("unroll") for (int n = 0; n < 2; ++n) _Pragma("unroll") for (int k = 0; k < 2; ++k) \
;         acc[ai][bj][m][n] = __builtin_amdgcn_mfma_f32_16x16x32_bf16(Bt[n][k], At[m][k], acc[ai][bj][m][n], 0, 0, 0); __builtin_amdgcn_s_setprio(0); } while (0)
; #define PG8_WAIT_V(n) asm volatile("s_waitcnt vmcnt(" #n ")" ::: "memory")
; #define PG8_WAIT_L(n) asm volatile("s_waitcnt lgkmcnt(" #n ")" ::: "memory")
; #define PG8_BAR __builtin_amdgcn_s_barrier()
; template <class Epi, class Sched>
; __device__ __forceinline__ void gemm_phase(int wv, LAS unsigned char* lds, const Gemm g, const Sched& S, const Epi& E) { LIDS
;     ...
;             PG8_LDB(B0, 0, 0); PG8_SCHED; PG8_LDA(At, 0, 0); PG8_STAGE(PG8_SA(1, 1), a1 + hstepA, voffA);
;             PG8_WAIT_L(8); PG8_BAR; PG8_WAIT_L(0); PG8_MMA(0, 0, At, B0); PG8_BAR; PG8_SCHED;
;             PG8_LDB(B1, 0, 1); PG8_STAGE(PG8_SB(0, 0), b2, voffB);
;             PG8_BAR; PG8_WAIT_L(0); PG8_MMA(0, 1, At, B1); PG8_BAR;
;             PG8_LDA(At, 0, 1); PG8_STAGE(PG8_SA(0, 0), a2, voffA);
;             PG8_BAR; PG8_WAIT_L(0); PG8_MMA(1, 0, At, B0); PG8_BAR; PG8_SCHED;
;             PG8_STAGE(PG8_SB(0, 1), b2 + hstepB, voffB);
;             PG8_WAIT_V(6); PG8_BAR; PG8_MMA(1, 1, At, B1); PG8_BAR;
;             PG8_LDB(B0, 1, 0); PG8_SCHED; PG8_LDA(At, 1, 0); PG8_STAGE(PG8_SA(0, 1), a2 + hstepA, voffA);
;             PG8_WAIT_L(8); PG8_BAR; PG8_WAIT_L(0); PG8_MMA(0, 0, At, B0); PG8_BAR; PG8_SCHED;
	s_waitcnt lgkmcnt(0)
	s_setprio 1
	s_waitcnt lgkmcnt(0)
	v_mfma_f32_16x16x32_bf16 v[52:55], v[108:111], v[128:131], v[52:55]
	v_mfma_f32_16x16x32_bf16 v[56:59], v[116:119], v[128:131], v[56:59]
	v_mfma_f32_16x16x32_bf16 v[60:63], v[108:111], v[164:167], v[60:63]
	v_mfma_f32_16x16x32_bf16 v[64:67], v[116:119], v[164:167], v[64:67]
	v_mfma_f32_16x16x32_bf16 v[68:71], v[108:111], v[172:175], v[68:71]
	v_mfma_f32_16x16x32_bf16 v[72:75], v[116:119], v[172:175], v[72:75]
	v_mfma_f32_16x16x32_bf16 v[76:79], v[108:111], v[198:201], v[76:79]
	v_mfma_f32_16x16x32_bf16 v[80:83], v[116:119], v[198:201], v[80:83]
	v_mfma_f32_16x16x32_bf16 v[52:55], v[112:115], v[136:139], v[52:55]
	v_mfma_f32_16x16x32_bf16 v[56:59], v[120:123], v[136:139], v[56:59]
	v_mfma_f32_16x16x32_bf16 v[60:63], v[112:115], v[168:171], v[60:63]
	v_mfma_f32_16x16x32_bf16 v[64:67], v[120:123], v[168:171], v[64:67]
	v_mfma_f32_16x16x32_bf16 v[68:71], v[112:115], v[194:197], v[68:71]
	v_mfma_f32_16x16x32_bf16 v[72:75], v[120:123], v[194:197], v[72:75]
	v_mfma_f32_16x16x32_bf16 v[76:79], v[112:115], v[202:205], v[76:79]
	v_mfma_f32_16x16x32_bf16 v[80:83], v[120:123], v[202:205], v[80:83]
	s_setprio 0
	s_barrier
	s_mov_b64 s[26:27], s[78:79]
	ds_read_b128 v[206:209], v178
	ds_read_b128 v[218:221], v178 offset:1024
	ds_read_b128 v[222:225], v178 offset:2048
	ds_read_b128 v[226:229], v178 offset:3072
	s_mov_b32 m0, s20
	v_lshl_add_u64 v[132:133], s[26:27], 0, v[126:127]
	s_add_u32 s26, s78, 0x8000
	s_addc_u32 s27, s79, 0
	global_load_lds_dwordx4 v[132:133], off
	s_mov_b32 m0, s11
	v_lshl_add_u64 v[132:133], s[26:27], 0, v[126:127]
	global_load_lds_dwordx4 v[132:133], off
	s_barrier
	s_waitcnt lgkmcnt(0)
	s_setprio 1
	s_waitcnt lgkmcnt(0)
	v_mfma_f32_16x16x32_bf16 v[100:103], v[206:209], v[128:131], v[100:103]
	v_mfma_f32_16x16x32_bf16 v[20:23], v[222:225], v[128:131], v[20:23]
	v_mfma_f32_16x16x32_bf16 v[24:27], v[206:209], v[164:167], v[24:27]
	v_mfma_f32_16x16x32_bf16 v[28:31], v[222:225], v[164:167], v[28:31]
	v_mfma_f32_16x16x32_bf16 v[32:35], v[206:209], v[172:175], v[32:35]
	v_mfma_f32_16x16x32_bf16 v[36:39], v[222:225], v[172:175], v[36:39]
	v_mfma_f32_16x16x32_bf16 v[40:43], v[206:209], v[198:201], v[40:43]
	v_mfma_f32_16x16x32_bf16 v[44:47], v[222:225], v[198:201], v[44:47]
	v_mfma_f32_16x16x32_bf16 v[230:233], v[218:221], v[136:139], v[100:103]
	v_mfma_f32_16x16x32_bf16 v[20:23], v[226:229], v[136:139], v[20:23]
	v_mfma_f32_16x16x32_bf16 v[24:27], v[218:221], v[168:171], v[24:27]
	v_mfma_f32_16x16x32_bf16 v[28:31], v[226:229], v[168:171], v[28:31]
	v_mfma_f32_16x16x32_bf16 v[32:35], v[218:221], v[194:197], v[32:35]
	v_mfma_f32_16x16x32_bf16 v[36:39], v[226:229], v[194:197], v[36:39]
	v_mfma_f32_16x16x32_bf16 v[40:43], v[218:221], v[202:205], v[40:43]
	v_mfma_f32_16x16x32_bf16 v[44:47], v[226:229], v[202:205], v[44:47]
	s_setprio 0
	s_mov_b64 s[26:27], s[72:73]
	s_barrier
	ds_read_b128 v[100:103], v135 offset:16384
	ds_read_b128 v[128:131], v135 offset:17408
	ds_read_b128 v[136:139], v135 offset:18432
	ds_read_b128 v[164:167], v135 offset:19456
	ds_read_b128 v[168:171], v135 offset:20480
	ds_read_b128 v[172:175], v135 offset:21504
	ds_read_b128 v[194:197], v135 offset:22528
	ds_read_b128 v[198:201], v135 offset:23552
	s_mov_b32 m0, s58
	v_lshl_add_u64 v[132:133], s[26:27], 0, v[124:125]
	s_add_u32 s26, s72, 0x80000
	s_addc_u32 s27, s73, 0
	global_load_lds_dwordx4 v[132:133], off
	s_mov_b32 m0, s77
	v_lshl_add_u64 v[132:133], s[26:27], 0, v[124:125]
	global_load_lds_dwordx4 v[132:133], off
	s_barrier
	s_waitcnt lgkmcnt(0)
	s_setprio 1
	s_waitcnt lgkmcnt(0)
	v_mfma_f32_16x16x32_bf16 v[140:143], v[108:111], v[100:103], v[140:143]
	v_mfma_f32_16x16x32_bf16 v[144:147], v[116:119], v[100:103], v[144:147]
	v_mfma_f32_16x16x32_bf16 v[148:151], v[108:111], v[136:139], v[148:151]
	v_mfma_f32_16x16x32_bf16 v[152:155], v[116:119], v[136:139], v[152:155]
	v_mfma_f32_16x16x32_bf16 v[156:159], v[108:111], v[168:171], v[156:159]
	v_mfma_f32_16x16x32_bf16 v[160:163], v[116:119], v[168:171], v[160:163]
	v_mfma_f32_16x16x32_bf16 v[4:7], v[108:111], v[194:197], v[4:7]
	v_mfma_f32_16x16x32_bf16 v[8:11], v[116:119], v[194:197], v[8:11]
	v_mfma_f32_16x16x32_bf16 v[140:143], v[112:115], v[128:131], v[140:143]
	v_mfma_f32_16x16x32_bf16 v[144:147], v[120:123], v[128:131], v[144:147]
	v_mfma_f32_16x16x32_bf16 v[148:151], v[112:115], v[164:167], v[148:151]
	v_mfma_f32_16x16x32_bf16 v[152:155], v[120:123], v[164:167], v[152:155]
	v_mfma_f32_16x16x32_bf16 v[156:159], v[112:115], v[172:175], v[156:159]
	v_mfma_f32_16x16x32_bf16 v[160:163], v[120:123], v[172:175], v[160:163]
	v_mfma_f32_16x16x32_bf16 v[4:7], v[112:115], v[198:201], v[4:7]
	v_mfma_f32_16x16x32_bf16 v[8:11], v[120:123], v[198:201], v[8:11]
	s_setprio 0
	s_barrier
	s_add_u32 s20, s78, 0x10000
	s_mov_b32 m0, s21
	s_addc_u32 s21, s79, 0
	s_nop 0
	v_lshl_add_u64 v[108:109], s[20:21], 0, v[126:127]
	s_add_u32 s20, s78, 0x18000
	s_addc_u32 s21, s79, 0
	global_load_lds_dwordx4 v[108:109], off
	s_mov_b32 m0, s17
	v_lshl_add_u64 v[108:109], s[20:21], 0, v[126:127]
	global_load_lds_dwordx4 v[108:109], off
	s_waitcnt vmcnt(6)
	s_barrier
; #define PG8_STAGE(bufoff, gbase, voff) do { _Pragma("unroll") for (int _i = 0; _i < 2; ++_i) { const char* _gb = (const char*)(gbase) + (size_t)_i * (voff##_q); asm volatile("" : "+s"(_gb)); \
;         __builtin_amdgcn_global_load_lds((const unsigned*)(_gb + (voff)), (LAS unsigned*)(lds + (bufoff) + ldsw + _i * 8192), 16, 0, 0); } } while (0)
; #define PG8_LDA(dst, b, h) do { _Pragma("unroll") for (int m = 0; m < 4; ++m) _Pragma("unroll") for (int k = 0; k < 2; ++k) dst[m][k] = *(const LAS bf16x8*)(lds + PG8_SA(b, h) + aoff + m * 2048 + k * 1024); } while (0)
; #define PG8_LDB(dst, b, h) do { _Pragma("unroll") for (int n = 0; n < 2; ++n) _Pragma("unroll") for (int k = 0; k < 2; ++k) dst[n][k] = *(const LAS bf16x8*)(lds + PG8_SB(b, h) + boff + n * 2048 + k * 1024); } while (0)
; #define PG8_MMA(ai, bj, At, Bt) do { __builtin_amdgcn_s_setprio(1); _Pragma("unroll") for (int m = 0; m < 4; ++m) _Pragma("unroll") for (int n = 0; n < 2; ++n) _Pragma("unroll") for (int k = 0; k < 2; ++k) \
;         acc[ai][bj][m][n] = __builtin_amdgcn_mfma_f32_16x16x32_bf16(Bt[n][k], At[m][k], acc[ai][bj][m][n], 0, 0, 0); __builtin_amdgcn_s_setprio(0); } while (0)
; #define PG8_WAIT_V(n) asm volatile("s_waitcnt vmcnt(" #n ")" ::: "memory")
; #define PG8_WAIT_L(n) asm volatile("s_waitcnt lgkmcnt(" #n ")" ::: "memory")
; #define PG8_BAR __builtin_amdgcn_s_barrier()
; #define PG8_SCHED __builtin_amdgcn_sched_barrier(0)
; template <class Epi, class Sched>
; __device__ __forceinline__ void gemm_phase(int wv, LAS unsigned char* lds, const Gemm g, const Sched& S, const Epi& E) { LIDS
;     ...
;             PG8_WAIT_V(6); PG8_BAR; PG8_MMA(1, 1, At, B1); PG8_BAR;
;             PG8_LDB(B0, 1, 0); PG8_SCHED; PG8_LDA(At, 1, 0); PG8_STAGE(PG8_SA(0, 1), a2 + hstepA, voffA);
;             PG8_WAIT_L(8); PG8_BAR; PG8_WAIT_L(0); PG8_MMA(0, 0, At, B0); PG8_BAR; PG8_SCHED;
;             PG8_LDB(B1, 1, 1); PG8_STAGE(PG8_SB(1, 0), b3, voffB);
;             PG8_BAR; PG8_WAIT_L(0); PG8_MMA(0, 1, At, B1); PG8_BAR;
;             PG8_LDA(At, 1, 1); PG8_STAGE(PG8_SA(1, 0), a3, voffA);
;             PG8_BAR; PG8_WAIT_L(0); PG8_MMA(1, 0, At, B0); PG8_BAR; PG8_SCHED;
;             PG8_STAGE(PG8_SB(1, 1), b3 + hstepB, voffB);
;             PG8_WAIT_V(6); PG8_BAR; PG8_MMA(1, 1, At, B1); PG8_BAR;
	s_setprio 1
	v_mfma_f32_16x16x32_bf16 v[12:15], v[206:209], v[100:103], v[12:15]
	v_mfma_f32_16x16x32_bf16 v[16:19], v[222:225], v[100:103], v[16:19]
	v_mfma_f32_16x16x32_bf16 v[92:95], v[222:225], v[136:139], v[92:95]
	v_mfma_f32_16x16x32_bf16 v[12:15], v[218:221], v[128:131], v[12:15]
	v_mfma_f32_16x16x32_bf16 v[16:19], v[226:229], v[128:131], v[16:19]
	v_mfma_f32_16x16x32_bf16 v[128:131], v[226:229], v[164:167], v[92:95]
	v_mfma_f32_16x16x32_bf16 v[92:95], v[206:209], v[168:171], v[96:99]
	v_mfma_f32_16x16x32_bf16 v[84:87], v[206:209], v[194:197], v[84:87]
	v_mfma_f32_16x16x32_bf16 v[48:51], v[206:209], v[136:139], v[48:51]
	v_mfma_f32_16x16x32_bf16 v[136:139], v[218:221], v[172:175], v[92:95]
	v_mfma_f32_16x16x32_bf16 v[92:95], v[222:225], v[168:171], v[104:107]
	v_mfma_f32_16x16x32_bf16 v[168:171], v[218:221], v[198:201], v[84:87]
	v_mfma_f32_16x16x32_bf16 v[84:87], v[222:225], v[194:197], v[88:91]
	v_mfma_f32_16x16x32_bf16 v[48:51], v[218:221], v[164:167], v[48:51]
	v_mfma_f32_16x16x32_bf16 v[164:167], v[226:229], v[172:175], v[92:95]
	v_mfma_f32_16x16x32_bf16 v[172:175], v[226:229], v[198:201], v[84:87]
	s_setprio 0
	s_barrier
	ds_read_b128 v[194:197], v179
	ds_read_b128 v[198:201], v179 offset:1024
	ds_read_b128 v[202:205], v179 offset:2048
	ds_read_b128 v[206:209], v179 offset:3072
	s_add_u32 s20, s72, 0x100000
	s_addc_u32 s21, s73, 0
	ds_read_b128 v[92:95], v135 offset:32768
	ds_read_b128 v[96:99], v135 offset:33792
	ds_read_b128 v[112:115], v135 offset:34816
	ds_read_b128 v[218:221], v135 offset:35840
	ds_read_b128 v[222:225], v135 offset:36864
	ds_read_b128 v[226:229], v135 offset:37888
	ds_read_b128 v[234:237], v135 offset:38912
	ds_read_b128 v[238:241], v135 offset:39936
	s_mov_b32 m0, s82
	v_lshl_add_u64 v[84:85], s[20:21], 0, v[124:125]
	s_add_u32 s20, s72, 0x180000
	s_addc_u32 s21, s73, 0
	global_load_lds_dwordx4 v[84:85], off
	s_mov_b32 m0, s56
	v_lshl_add_u64 v[84:85], s[20:21], 0, v[124:125]
	global_load_lds_dwordx4 v[84:85], off
	s_waitcnt lgkmcnt(8)
	s_barrier
	s_waitcnt lgkmcnt(0)
	s_setprio 1
	s_waitcnt lgkmcnt(0)
	v_mfma_f32_16x16x32_bf16 v[52:55], v[194:197], v[92:95], v[52:55]
	v_mfma_f32_16x16x32_bf16 v[242:245], v[198:201], v[96:99], v[52:55]
	v_mfma_f32_16x16x32_bf16 v[52:55], v[202:205], v[92:95], v[56:59]
	v_mfma_f32_16x16x32_bf16 v[246:249], v[206:209], v[96:99], v[52:55]
	v_mfma_f32_16x16x32_bf16 v[52:55], v[194:197], v[112:115], v[60:63]
	v_mfma_f32_16x16x32_bf16 v[100:103], v[198:201], v[218:221], v[52:55]
	v_mfma_f32_16x16x32_bf16 v[52:55], v[202:205], v[112:115], v[64:67]
	v_mfma_f32_16x16x32_bf16 v[104:107], v[206:209], v[218:221], v[52:55]
	v_mfma_f32_16x16x32_bf16 v[52:55], v[194:197], v[222:225], v[68:71]
	v_mfma_f32_16x16x32_bf16 v[84:87], v[198:201], v[226:229], v[52:55]
	v_mfma_f32_16x16x32_bf16 v[52:55], v[202:205], v[222:225], v[72:75]
	v_mfma_f32_16x16x32_bf16 v[88:91], v[206:209], v[226:229], v[52:55]
	v_mfma_f32_16x16x32_bf16 v[52:55], v[194:197], v[234:237], v[76:79]
	v_mfma_f32_16x16x32_bf16 v[68:71], v[198:201], v[238:241], v[52:55]
	v_mfma_f32_16x16x32_bf16 v[52:55], v[202:205], v[234:237], v[80:83]
	v_mfma_f32_16x16x32_bf16 v[72:75], v[206:209], v[238:241], v[52:55]
	s_setprio 0
	s_barrier
	s_mov_b64 s[20:21], s[90:91]
	ds_read_b128 v[182:185], v190
	ds_read_b128 v[178:181], v190 offset:1024
	ds_read_b128 v[186:189], v190 offset:2048
	ds_read_b128 v[190:193], v190 offset:3072
	s_mov_b32 m0, s23
	v_lshl_add_u64 v[52:53], s[20:21], 0, v[126:127]
	s_add_u32 s20, s90, 0x8000
	s_addc_u32 s21, s91, 0
	global_load_lds_dwordx4 v[52:53], off
	s_mov_b32 m0, s18
	v_lshl_add_u64 v[52:53], s[20:21], 0, v[126:127]
	global_load_lds_dwordx4 v[52:53], off
	s_barrier
	s_waitcnt lgkmcnt(0)
	s_setprio 1
	s_waitcnt lgkmcnt(0)
	v_mfma_f32_16x16x32_bf16 v[20:23], v[186:189], v[92:95], v[20:23]
	v_mfma_f32_16x16x32_bf16 v[120:123], v[190:193], v[96:99], v[20:23]
	v_mfma_f32_16x16x32_bf16 v[20:23], v[182:185], v[112:115], v[24:27]
	v_mfma_f32_16x16x32_bf16 v[108:111], v[178:181], v[218:221], v[20:23]
	v_mfma_f32_16x16x32_bf16 v[20:23], v[186:189], v[112:115], v[28:31]
	v_mfma_f32_16x16x32_bf16 v[112:115], v[190:193], v[218:221], v[20:23]
	v_mfma_f32_16x16x32_bf16 v[20:23], v[182:185], v[222:225], v[32:35]
	v_mfma_f32_16x16x32_bf16 v[52:55], v[182:185], v[92:95], v[230:233]
	v_mfma_f32_16x16x32_bf16 v[92:95], v[178:181], v[226:229], v[20:23]
	v_mfma_f32_16x16x32_bf16 v[20:23], v[186:189], v[222:225], v[36:39]
	v_mfma_f32_16x16x32_bf16 v[116:119], v[178:181], v[96:99], v[52:55]
	v_mfma_f32_16x16x32_bf16 v[96:99], v[190:193], v[226:229], v[20:23]
	v_mfma_f32_16x16x32_bf16 v[20:23], v[182:185], v[234:237], v[40:43]
	v_mfma_f32_16x16x32_bf16 v[76:79], v[178:181], v[238:241], v[20:23]
	v_mfma_f32_16x16x32_bf16 v[20:23], v[186:189], v[234:237], v[44:47]
	v_mfma_f32_16x16x32_bf16 v[80:83], v[190:193], v[238:241], v[20:23]
	s_setprio 0
	s_mov_b64 s[20:21], s[84:85]
	s_barrier
	ds_read_b128 v[28:31], v135 offset:49152
	ds_read_b128 v[32:35], v135 offset:50176
	ds_read_b128 v[218:221], v135 offset:51200
	ds_read_b128 v[222:225], v135 offset:52224
	ds_read_b128 v[226:229], v135 offset:53248
	ds_read_b128 v[230:233], v135 offset:54272
	ds_read_b128 v[234:237], v135 offset:55296
	ds_read_b128 v[238:241], v135 offset:56320
	s_mov_b32 m0, s0
	v_lshl_add_u64 v[20:21], s[20:21], 0, v[124:125]
	s_add_u32 s20, s84, 0x80000
	s_addc_u32 s21, s85, 0
	global_load_lds_dwordx4 v[20:21], off
	s_mov_b32 m0, s59
	v_lshl_add_u64 v[20:21], s[20:21], 0, v[124:125]
	global_load_lds_dwordx4 v[20:21], off
	s_barrier
; __device__ __forceinline__ u32x4 pack8(f32x4 a, f32x4 b) { u32x4 r; r[0] = cvt_pk_bf16(a[0], a[1]); r[1] = cvt_pk_bf16(a[2], a[3]); r[2] = cvt_pk_bf16(b[0], b[1]); r[3] = cvt_pk_bf16(b[2], b[3]); return r; }
; __device__ __forceinline__ int lane_id_asm() { int x; asm volatile("v_mbcnt_lo_u32_b32 %0, -1, 0\n\tv_mbcnt_hi_u32_b32 %0, -1, %0" : "=&v"(x)); return x; }
; #define PG8_STAGE(bufoff, gbase, voff) do { _Pragma("unroll") for (int _i = 0; _i < 2; ++_i) { const char* _gb = (const char*)(gbase) + (size_t)_i * (voff##_q); asm volatile("" : "+s"(_gb)); \
;         __builtin_amdgcn_global_load_lds((const unsigned*)(_gb + (voff)), (LAS unsigned*)(lds + (bufoff) + ldsw + _i * 8192), 16, 0, 0); } } while (0)
; #define PG8_MMA(ai, bj, At, Bt) do { __builtin_amdgcn_s_setprio(1); _Pragma("unroll") for (int m = 0; m < 4; ++m) _Pragma("unroll") for (int n = 0; n < 2; ++n) _Pragma("unroll") for (int k = 0; k < 2; ++k) \
;         acc[ai][bj][m][n] = __builtin_amdgcn_mfma_f32_16x16x32_bf16(Bt[n][k], At[m][k], acc[ai][bj][m][n], 0, 0, 0); __builtin_amdgcn_s_setprio(0); } while (0)
; #define PG8_BAR __builtin_amdgcn_s_barrier()
; template <class Epi, class Sched>
; __device__ __forceinline__ void gemm_phase(int wv, LAS unsigned char* lds, const Gemm g, const Sched& S, const Epi& E) { LIDS
;     ...
;             PG8_BAR; PG8_WAIT_L(0); PG8_MMA(1, 0, At, B0); PG8_BAR; PG8_SCHED;
;             PG8_STAGE(PG8_SB(1, 1), b3 + hstepB, voffB);
;             PG8_WAIT_V(6); PG8_BAR; PG8_MMA(1, 1, At, B1); PG8_BAR;
;         }
;         { const int l2 = lane_id_asm(); E(acc, cur, wr, wc, l2 & 15, l2 >> 4); }
;     __device__ __forceinline__ void operator()(const AccT& acc, const Unit& u, int wr, int wc, int fr, int fq) const {
;         EPI_ROWS(u)
; #pragma unroll
;         for (int ai = 0; ai < 2; ++ai)
; #pragma unroll
;             for (int m = 0; m < 4; ++m) {
;                 const int row = row0 + ai * HALF + m * 16;
;                 const f32x4 pc = *(const f32x4*)(ssp + (size_t)row * 16 + 8);
;                 const float sc = rsqrtf(((pc[0] + pc[1]) + (pc[2] + pc[3])) * (1.0f / 256.0f) + EPS);
; #pragma unroll
;                 for (int bj = 0; bj < 2; ++bj) {
;                     const int col = colbase + bj * HALF, head = col >> 7, d = col & 127;
;                     *(u32x4*)(Kf + (size_t)row * NKF + head * 192 + d) = pack8(acc[ai][bj][m][0] * sc, acc[ai][bj][m][1] * sc);
	s_waitcnt lgkmcnt(0)
	s_setprio 1
	s_waitcnt lgkmcnt(0)
	v_mfma_f32_16x16x32_bf16 v[20:23], v[194:197], v[28:31], v[140:143]
	v_mfma_f32_16x16x32_bf16 v[52:55], v[198:201], v[32:35], v[20:23]
	v_mfma_f32_16x16x32_bf16 v[20:23], v[202:205], v[28:31], v[144:147]
	v_mfma_f32_16x16x32_bf16 v[56:59], v[206:209], v[32:35], v[20:23]
	v_mfma_f32_16x16x32_bf16 v[20:23], v[194:197], v[218:221], v[148:151]
	v_mfma_f32_16x16x32_bf16 v[36:39], v[198:201], v[222:225], v[20:23]
	v_mfma_f32_16x16x32_bf16 v[20:23], v[202:205], v[218:221], v[152:155]
	v_mfma_f32_16x16x32_bf16 v[40:43], v[206:209], v[222:225], v[20:23]
	v_mfma_f32_16x16x32_bf16 v[20:23], v[194:197], v[226:229], v[156:159]
	v_mfma_f32_16x16x32_bf16 v[24:27], v[202:205], v[226:229], v[160:163]
	v_mfma_f32_16x16x32_bf16 v[4:7], v[194:197], v[234:237], v[4:7]
	v_mfma_f32_16x16x32_bf16 v[8:11], v[202:205], v[234:237], v[8:11]
	v_mfma_f32_16x16x32_bf16 v[20:23], v[198:201], v[230:233], v[20:23]
	v_mfma_f32_16x16x32_bf16 v[24:27], v[206:209], v[230:233], v[24:27]
	v_mfma_f32_16x16x32_bf16 v[4:7], v[198:201], v[238:241], v[4:7]
	v_mfma_f32_16x16x32_bf16 v[8:11], v[206:209], v[238:241], v[8:11]
	s_setprio 0
	s_barrier
	s_add_u32 s20, s90, 0x10000
	s_addc_u32 s21, s91, 0
	s_mov_b32 m0, s24
	v_lshl_add_u64 v[44:45], s[20:21], 0, v[126:127]
	s_add_u32 s20, s90, 0x18000
	s_addc_u32 s21, s91, 0
	global_load_lds_dwordx4 v[44:45], off
	s_mov_b32 m0, s19
	v_lshl_add_u64 v[44:45], s[20:21], 0, v[126:127]
	global_load_lds_dwordx4 v[44:45], off
	s_waitcnt vmcnt(6)
	s_barrier
	s_setprio 1
	v_mfma_f32_16x16x32_bf16 v[12:15], v[182:185], v[28:31], v[12:15]
	v_mfma_f32_16x16x32_bf16 v[60:63], v[178:181], v[32:35], v[12:15]
	v_mfma_f32_16x16x32_bf16 v[12:15], v[186:189], v[28:31], v[16:19]
	v_mfma_f32_16x16x32_bf16 v[64:67], v[190:193], v[32:35], v[12:15]
	v_mfma_f32_16x16x32_bf16 v[12:15], v[182:185], v[218:221], v[48:51]
	v_mfma_f32_16x16x32_bf16 v[44:47], v[178:181], v[222:225], v[12:15]
	v_mfma_f32_16x16x32_bf16 v[12:15], v[186:189], v[218:221], v[128:131]
	v_mfma_f32_16x16x32_bf16 v[48:51], v[190:193], v[222:225], v[12:15]
	v_mfma_f32_16x16x32_bf16 v[12:15], v[182:185], v[226:229], v[136:139]
	v_mfma_f32_16x16x32_bf16 v[28:31], v[178:181], v[230:233], v[12:15]
	v_mfma_f32_16x16x32_bf16 v[12:15], v[186:189], v[226:229], v[164:167]
	v_mfma_f32_16x16x32_bf16 v[32:35], v[190:193], v[230:233], v[12:15]
	v_mfma_f32_16x16x32_bf16 v[12:15], v[182:185], v[234:237], v[168:171]
	v_mfma_f32_16x16x32_bf16 v[16:19], v[186:189], v[234:237], v[172:175]
	v_mfma_f32_16x16x32_bf16 v[12:15], v[178:181], v[238:241], v[12:15]
	v_mfma_f32_16x16x32_bf16 v[16:19], v[190:193], v[238:241], v[16:19]
	s_setprio 0
	s_lshl_b32 s9, s68, 8
	s_barrier
	v_mbcnt_lo_u32_b32 v129, -1, 0
	v_mbcnt_hi_u32_b32 v129, -1, v129
	s_add_i32 s9, s9, s83
	v_and_or_b32 v128, v129, 15, s9
	s_lshl_b32 s9, s16, 8
	v_ashrrev_i32_e32 v129, 1, v129
	s_or_b32 s9, s9, s92
	v_and_b32_e32 v129, -8, v129
	v_add_u32_e32 v141, s9, v129
	v_ashrrev_i32_e32 v129, 31, v128
	v_readlane_b32 s18, v253, 12
	v_lshlrev_b64 v[130:131], 6, v[128:129]
	v_readlane_b32 s19, v253, 13
	v_ashrrev_i32_e32 v144, 7, v141
	s_movk_i32 s9, 0xc0
	v_lshl_add_u64 v[130:131], s[18:19], 0, v[130:131]
	global_load_dword v210, v[130:131], off offset:1056
	global_load_dword v211, v[130:131], off offset:2080
	global_load_dword v210, v[130:131], off offset:3104
	v_add_co_u32_e32 v212, vcc, 0x2000, v130
	s_nop 1
	v_addc_co_u32_e32 v213, vcc, 0, v131, vcc
	global_load_dword v211, v[212:213], off offset:32
	global_load_dword v210, v[212:213], off offset:1056
	global_load_dword v211, v[212:213], off offset:2080
	global_load_dword v210, v[212:213], off offset:3104
	global_load_dwordx4 v[130:133], v[130:131], off offset:32
	v_and_b32_e32 v146, 0x78, v141
	v_lshlrev_b32_e32 v176, 1, v146
	s_add_i32 s69, s69, s55
	s_mov_b32 s68, s10
	s_mov_b64 s[90:91], s[62:63]
	s_mov_b64 s[86:87], s[12:13]
	s_waitcnt vmcnt(0)
	v_mov_b32_e32 v136, v131
	v_mov_b32_e32 v137, v132
	v_mov_b32_e32 v131, v133
	v_pk_add_f32 v[130:131], v[136:137], v[130:131]
	s_nop 0
	v_add_f32_e32 v129, v130, v131
	v_fmamk_f32 v129, v129, 0x3b800000, v252
	v_cmp_gt_f32_e32 vcc, s53, v129
	v_mul_f32_e32 v130, 0x4b800000, v129
	s_nop 0
	v_cndmask_b32_e32 v129, v129, v130, vcc
	v_rsq_f32_e32 v129, v129
	s_nop 0
	v_mul_f32_e32 v130, 0x45800000, v129
	v_cndmask_b32_e32 v140, v129, v130, vcc
	v_pk_mul_f32 v[132:133], v[242:243], v[140:141] op_sel_hi:[1,0]
	v_pk_mul_f32 v[130:131], v[244:245], v[140:141] op_sel_hi:[1,0]
	v_cvt_pk_bf16_f32 v136, v132, v133
	v_mul_lo_u32 v132, v144, s9
	v_pk_mul_f32 v[142:143], v[248:249], v[140:141] op_sel_hi:[1,0]
	v_pk_mul_f32 v[138:139], v[246:247], v[140:141] op_sel_hi:[1,0]
	v_cvt_pk_bf16_f32 v137, v130, v131
	v_mov_b64_e32 v[130:131], s[30:31]
	v_ashrrev_i32_e32 v133, 31, v132
	v_cvt_pk_bf16_f32 v138, v138, v139
	v_cvt_pk_bf16_f32 v139, v142, v143
	v_mad_i64_i32 v[142:143], s[16:17], v128, s52, v[130:131]
	v_lshlrev_b64 v[132:133], 1, v[132:133]
	v_lshl_add_u64 v[144:145], v[142:143], 0, v[132:133]
	v_add_u32_e32 v129, 0x80, v141
	v_lshl_add_u64 v[144:145], v[144:145], 0, v[176:177]
	v_ashrrev_i32_e32 v129, 7, v129
	v_pk_mul_f32 v[116:117], v[116:117], v[140:141] op_sel_hi:[1,0]
	global_store_dwordx4 v[144:145], v[136:139], off
	v_pk_mul_f32 v[122:123], v[122:123], v[140:141] op_sel_hi:[1,0]
	v_pk_mul_f32 v[120:121], v[120:121], v[140:141] op_sel_hi:[1,0]
	v_pk_mul_f32 v[136:137], v[118:119], v[140:141] op_sel_hi:[1,0]
	v_cvt_pk_bf16_f32 v118, v116, v117
	v_mul_lo_u32 v116, v129, s9
	v_ashrrev_i32_e32 v117, 31, v116
	v_lshlrev_b64 v[116:117], 1, v[116:117]
	v_cvt_pk_bf16_f32 v119, v136, v137
	v_cvt_pk_bf16_f32 v120, v120, v121
	v_cvt_pk_bf16_f32 v121, v122, v123
	v_lshl_add_u64 v[122:123], v[142:143], 0, v[116:117]
	v_lshl_add_u64 v[122:123], v[122:123], 0, v[176:177]
	global_store_dwordx4 v[122:123], v[118:121], off
	v_or_b32_e32 v122, 16, v128
	v_ashrrev_i32_e32 v123, 31, v122
	v_lshlrev_b64 v[118:119], 6, v[122:123]
	v_lshl_add_u64 v[118:119], s[18:19], 0, v[118:119]
	global_load_dwordx4 v[118:121], v[118:119], off offset:32
	s_waitcnt vmcnt(0)
; __device__ __forceinline__ u32x4 pack8(f32x4 a, f32x4 b) { u32x4 r; r[0] = cvt_pk_bf16(a[0], a[1]); r[1] = cvt_pk_bf16(a[2], a[3]); r[2] = cvt_pk_bf16(b[0], b[1]); r[3] = cvt_pk_bf16(b[2], b[3]); return r; }
;     __device__ __forceinline__ void operator()(const AccT& acc, const Unit& u, int wr, int wc, int fr, int fq) const {
;     ...
;         for (int ai = 0; ai < 2; ++ai)
; #pragma unroll
;             for (int m = 0; m < 4; ++m) {
;                 const int row = row0 + ai * HALF + m * 16;
;                 const f32x4 pc = *(const f32x4*)(ssp + (size_t)row * 16 + 8);
;                 const float sc = rsqrtf(((pc[0] + pc[1]) + (pc[2] + pc[3])) * (1.0f / 256.0f) + EPS);
; #pragma unroll
;                 for (int bj = 0; bj < 2; ++bj) {
;                     const int col = colbase + bj * HALF, head = col >> 7, d = col & 127;
;                     *(u32x4*)(Kf + (size_t)row * NKF + head * 192 + d) = pack8(acc[ai][bj][m][0] * sc, acc[ai][bj][m][1] * sc);
	v_mov_b32_e32 v136, v119
	v_mov_b32_e32 v137, v120
	v_mov_b32_e32 v119, v121
	v_pk_add_f32 v[118:119], v[136:137], v[118:119]
	s_nop 0
	v_add_f32_e32 v118, v118, v119
	v_fmamk_f32 v118, v118, 0x3b800000, v252
	v_cmp_gt_f32_e32 vcc, s53, v118
	v_mul_f32_e32 v119, 0x4b800000, v118
	s_nop 0
	v_cndmask_b32_e32 v118, v118, v119, vcc
	v_rsq_f32_e32 v118, v118
	s_nop 0
	v_mul_f32_e32 v119, 0x45800000, v118
	v_cndmask_b32_e32 v118, v118, v119, vcc
	v_pk_mul_f32 v[102:103], v[102:103], v[118:119] op_sel_hi:[1,0]
	v_pk_mul_f32 v[100:101], v[100:101], v[118:119] op_sel_hi:[1,0]
	v_pk_mul_f32 v[104:105], v[104:105], v[118:119] op_sel_hi:[1,0]
	v_pk_mul_f32 v[106:107], v[106:107], v[118:119] op_sel_hi:[1,0]
	v_cvt_pk_bf16_f32 v100, v100, v101
	v_cvt_pk_bf16_f32 v101, v102, v103
	v_cvt_pk_bf16_f32 v102, v104, v105
	v_mad_i64_i32 v[104:105], s[16:17], v122, s52, v[130:131]
	v_cvt_pk_bf16_f32 v103, v106, v107
	v_lshl_add_u64 v[106:107], v[104:105], 0, v[132:133]
	v_lshl_add_u64 v[106:107], v[106:107], 0, v[176:177]
	v_lshl_add_u64 v[104:105], v[104:105], 0, v[116:117]
	global_store_dwordx4 v[106:107], v[100:103], off
	v_lshl_add_u64 v[104:105], v[104:105], 0, v[176:177]
	v_pk_mul_f32 v[106:107], v[114:115], v[118:119] op_sel_hi:[1,0]
	v_pk_mul_f32 v[102:103], v[110:111], v[118:119] op_sel_hi:[1,0]
	v_pk_mul_f32 v[100:101], v[108:109], v[118:119] op_sel_hi:[1,0]
	v_pk_mul_f32 v[108:109], v[112:113], v[118:119] op_sel_hi:[1,0]
	v_cvt_pk_bf16_f32 v100, v100, v101
	v_cvt_pk_bf16_f32 v101, v102, v103
	s_nop 0
	v_cvt_pk_bf16_f32 v102, v108, v109
	v_cvt_pk_bf16_f32 v103, v106, v107
	global_store_dwordx4 v[104:105], v[100:103], off
	v_or_b32_e32 v104, 32, v128
	v_ashrrev_i32_e32 v105, 31, v104
	v_lshlrev_b64 v[100:101], 6, v[104:105]
	v_lshl_add_u64 v[100:101], s[18:19], 0, v[100:101]
	global_load_dwordx4 v[100:103], v[100:101], off offset:32
	s_waitcnt vmcnt(0)
	v_mov_b32_e32 v106, v101
	v_mov_b32_e32 v107, v102
	v_mov_b32_e32 v101, v103
	v_pk_add_f32 v[100:101], v[106:107], v[100:101]
	s_nop 0
	v_add_f32_e32 v100, v100, v101
	v_fmamk_f32 v100, v100, 0x3b800000, v252
	v_cmp_gt_f32_e32 vcc, s53, v100
	v_mul_f32_e32 v101, 0x4b800000, v100
	s_nop 0
	v_cndmask_b32_e32 v100, v100, v101, vcc
	v_rsq_f32_e32 v100, v100
	s_nop 0
	v_mul_f32_e32 v101, 0x45800000, v100
	v_cndmask_b32_e32 v100, v100, v101, vcc
	v_pk_mul_f32 v[86:87], v[86:87], v[100:101] op_sel_hi:[1,0]
	v_pk_mul_f32 v[84:85], v[84:85], v[100:101] op_sel_hi:[1,0]
	v_pk_mul_f32 v[88:89], v[88:89], v[100:101] op_sel_hi:[1,0]
	v_pk_mul_f32 v[90:91], v[90:91], v[100:101] op_sel_hi:[1,0]
	v_cvt_pk_bf16_f32 v84, v84, v85
	v_cvt_pk_bf16_f32 v85, v86, v87
	v_cvt_pk_bf16_f32 v86, v88, v89
	v_mad_i64_i32 v[88:89], s[16:17], v104, s52, v[130:131]
	v_cvt_pk_bf16_f32 v87, v90, v91
	v_lshl_add_u64 v[90:91], v[88:89], 0, v[132:133]
	v_lshl_add_u64 v[90:91], v[90:91], 0, v[176:177]
	v_lshl_add_u64 v[88:89], v[88:89], 0, v[116:117]
	global_store_dwordx4 v[90:91], v[84:87], off
	v_lshl_add_u64 v[88:89], v[88:89], 0, v[176:177]
	v_pk_mul_f32 v[90:91], v[98:99], v[100:101] op_sel_hi:[1,0]
	v_pk_mul_f32 v[86:87], v[94:95], v[100:101] op_sel_hi:[1,0]
	v_pk_mul_f32 v[84:85], v[92:93], v[100:101] op_sel_hi:[1,0]
	v_pk_mul_f32 v[92:93], v[96:97], v[100:101] op_sel_hi:[1,0]
	v_cvt_pk_bf16_f32 v84, v84, v85
	v_cvt_pk_bf16_f32 v85, v86, v87
	s_nop 0
	v_cvt_pk_bf16_f32 v86, v92, v93
	v_cvt_pk_bf16_f32 v87, v90, v91
	global_store_dwordx4 v[88:89], v[84:87], off
	v_or_b32_e32 v88, 48, v128
	v_ashrrev_i32_e32 v89, 31, v88
	v_lshlrev_b64 v[84:85], 6, v[88:89]
	v_lshl_add_u64 v[84:85], s[18:19], 0, v[84:85]
	global_load_dwordx4 v[84:87], v[84:85], off offset:32
	s_waitcnt vmcnt(0)
	v_mov_b32_e32 v90, v85
	v_mov_b32_e32 v91, v86
	v_mov_b32_e32 v85, v87
	v_pk_add_f32 v[84:85], v[90:91], v[84:85]
	s_nop 0
	v_add_f32_e32 v84, v84, v85
	v_fmamk_f32 v84, v84, 0x3b800000, v252
	v_cmp_gt_f32_e32 vcc, s53, v84
	v_mul_f32_e32 v85, 0x4b800000, v84
	s_nop 0
	v_cndmask_b32_e32 v84, v84, v85, vcc
	v_rsq_f32_e32 v84, v84
	s_nop 0
	v_mul_f32_e32 v85, 0x45800000, v84
	v_cndmask_b32_e32 v84, v84, v85, vcc
	v_pk_mul_f32 v[70:71], v[70:71], v[84:85] op_sel_hi:[1,0]
	v_pk_mul_f32 v[68:69], v[68:69], v[84:85] op_sel_hi:[1,0]
	v_pk_mul_f32 v[72:73], v[72:73], v[84:85] op_sel_hi:[1,0]
	v_pk_mul_f32 v[74:75], v[74:75], v[84:85] op_sel_hi:[1,0]
	v_cvt_pk_bf16_f32 v68, v68, v69
	v_cvt_pk_bf16_f32 v69, v70, v71
	v_cvt_pk_bf16_f32 v70, v72, v73
	v_mad_i64_i32 v[72:73], s[16:17], v88, s52, v[130:131]
	v_cvt_pk_bf16_f32 v71, v74, v75
	v_lshl_add_u64 v[74:75], v[72:73], 0, v[132:133]
	v_lshl_add_u64 v[74:75], v[74:75], 0, v[176:177]
	v_lshl_add_u64 v[72:73], v[72:73], 0, v[116:117]
	global_store_dwordx4 v[74:75], v[68:71], off
	v_lshl_add_u64 v[72:73], v[72:73], 0, v[176:177]
	v_pk_mul_f32 v[74:75], v[82:83], v[84:85] op_sel_hi:[1,0]
	v_pk_mul_f32 v[70:71], v[78:79], v[84:85] op_sel_hi:[1,0]
	v_pk_mul_f32 v[68:69], v[76:77], v[84:85] op_sel_hi:[1,0]
	v_pk_mul_f32 v[76:77], v[80:81], v[84:85] op_sel_hi:[1,0]
	v_cvt_pk_bf16_f32 v68, v68, v69
	v_cvt_pk_bf16_f32 v69, v70, v71
	s_nop 0
	v_cvt_pk_bf16_f32 v70, v76, v77
	v_cvt_pk_bf16_f32 v71, v74, v75
	global_store_dwordx4 v[72:73], v[68:71], off
	v_add_u32_e32 v72, 0x80, v128
	v_ashrrev_i32_e32 v73, 31, v72
	v_lshlrev_b64 v[68:69], 6, v[72:73]
	v_lshl_add_u64 v[68:69], s[18:19], 0, v[68:69]
	global_load_dwordx4 v[68:71], v[68:69], off offset:32
	s_waitcnt vmcnt(0)
; __device__ __forceinline__ u32x4 pack8(f32x4 a, f32x4 b) { u32x4 r; r[0] = cvt_pk_bf16(a[0], a[1]); r[1] = cvt_pk_bf16(a[2], a[3]); r[2] = cvt_pk_bf16(b[0], b[1]); r[3] = cvt_pk_bf16(b[2], b[3]); return r; }
;     __device__ __forceinline__ void operator()(const AccT& acc, const Unit& u, int wr, int wc, int fr, int fq) const {
;     ...
;         for (int ai = 0; ai < 2; ++ai)
; #pragma unroll
;             for (int m = 0; m < 4; ++m) {
;                 const int row = row0 + ai * HALF + m * 16;
;                 const f32x4 pc = *(const f32x4*)(ssp + (size_t)row * 16 + 8);
;                 const float sc = rsqrtf(((pc[0] + pc[1]) + (pc[2] + pc[3])) * (1.0f / 256.0f) + EPS);
; #pragma unroll
;                 for (int bj = 0; bj < 2; ++bj) {
;                     const int col = colbase + bj * HALF, head = col >> 7, d = col & 127;
;                     *(u32x4*)(Kf + (size_t)row * NKF + head * 192 + d) = pack8(acc[ai][bj][m][0] * sc, acc[ai][bj][m][1] * sc);
	v_mov_b32_e32 v74, v69
	v_mov_b32_e32 v75, v70
	v_mov_b32_e32 v69, v71
	v_pk_add_f32 v[68:69], v[74:75], v[68:69]
	s_nop 0
	v_add_f32_e32 v68, v68, v69
	v_fmamk_f32 v68, v68, 0x3b800000, v252
	v_cmp_gt_f32_e32 vcc, s53, v68
	v_mul_f32_e32 v69, 0x4b800000, v68
	s_nop 0
	v_cndmask_b32_e32 v68, v68, v69, vcc
	v_rsq_f32_e32 v68, v68
	s_nop 0
	v_mul_f32_e32 v69, 0x45800000, v68
	v_cndmask_b32_e32 v68, v68, v69, vcc
	v_pk_mul_f32 v[54:55], v[54:55], v[68:69] op_sel_hi:[1,0]
	v_pk_mul_f32 v[52:53], v[52:53], v[68:69] op_sel_hi:[1,0]
	v_pk_mul_f32 v[56:57], v[56:57], v[68:69] op_sel_hi:[1,0]
	v_pk_mul_f32 v[58:59], v[58:59], v[68:69] op_sel_hi:[1,0]
	v_cvt_pk_bf16_f32 v52, v52, v53
	v_cvt_pk_bf16_f32 v53, v54, v55
	v_cvt_pk_bf16_f32 v54, v56, v57
	v_mad_i64_i32 v[56:57], s[16:17], v72, s52, v[130:131]
	v_cvt_pk_bf16_f32 v55, v58, v59
	v_lshl_add_u64 v[58:59], v[56:57], 0, v[132:133]
	v_lshl_add_u64 v[58:59], v[58:59], 0, v[176:177]
	v_lshl_add_u64 v[56:57], v[56:57], 0, v[116:117]
	global_store_dwordx4 v[58:59], v[52:55], off
	v_lshl_add_u64 v[56:57], v[56:57], 0, v[176:177]
	v_pk_mul_f32 v[58:59], v[66:67], v[68:69] op_sel_hi:[1,0]
	v_pk_mul_f32 v[54:55], v[62:63], v[68:69] op_sel_hi:[1,0]
	v_pk_mul_f32 v[52:53], v[60:61], v[68:69] op_sel_hi:[1,0]
	v_pk_mul_f32 v[60:61], v[64:65], v[68:69] op_sel_hi:[1,0]
	v_cvt_pk_bf16_f32 v52, v52, v53
	v_cvt_pk_bf16_f32 v53, v54, v55
	s_nop 0
	v_cvt_pk_bf16_f32 v54, v60, v61
	v_cvt_pk_bf16_f32 v55, v58, v59
	global_store_dwordx4 v[56:57], v[52:55], off
	v_add_u32_e32 v56, 0x90, v128
	v_ashrrev_i32_e32 v57, 31, v56
	v_lshlrev_b64 v[52:53], 6, v[56:57]
	v_lshl_add_u64 v[52:53], s[18:19], 0, v[52:53]
	global_load_dwordx4 v[52:55], v[52:53], off offset:32
	s_waitcnt vmcnt(0)
	v_mov_b32_e32 v58, v53
	v_mov_b32_e32 v59, v54
	v_mov_b32_e32 v53, v55
	v_pk_add_f32 v[52:53], v[58:59], v[52:53]
	s_nop 0
	v_add_f32_e32 v52, v52, v53
	v_fmamk_f32 v52, v52, 0x3b800000, v252
	v_cmp_gt_f32_e32 vcc, s53, v52
	v_mul_f32_e32 v53, 0x4b800000, v52
	s_nop 0
	v_cndmask_b32_e32 v52, v52, v53, vcc
	v_rsq_f32_e32 v52, v52
	s_nop 0
	v_mul_f32_e32 v53, 0x45800000, v52
	v_cndmask_b32_e32 v52, v52, v53, vcc
	v_pk_mul_f32 v[38:39], v[38:39], v[52:53] op_sel_hi:[1,0]
	v_pk_mul_f32 v[36:37], v[36:37], v[52:53] op_sel_hi:[1,0]
	v_pk_mul_f32 v[40:41], v[40:41], v[52:53] op_sel_hi:[1,0]
	v_pk_mul_f32 v[42:43], v[42:43], v[52:53] op_sel_hi:[1,0]
	v_cvt_pk_bf16_f32 v36, v36, v37
	v_cvt_pk_bf16_f32 v37, v38, v39
	v_cvt_pk_bf16_f32 v38, v40, v41
	v_mad_i64_i32 v[40:41], s[16:17], v56, s52, v[130:131]
	v_cvt_pk_bf16_f32 v39, v42, v43
	v_lshl_add_u64 v[42:43], v[40:41], 0, v[132:133]
	v_lshl_add_u64 v[42:43], v[42:43], 0, v[176:177]
	v_lshl_add_u64 v[40:41], v[40:41], 0, v[116:117]
	global_store_dwordx4 v[42:43], v[36:39], off
	v_lshl_add_u64 v[40:41], v[40:41], 0, v[176:177]
	v_pk_mul_f32 v[42:43], v[50:51], v[52:53] op_sel_hi:[1,0]
	v_pk_mul_f32 v[38:39], v[46:47], v[52:53] op_sel_hi:[1,0]
	v_pk_mul_f32 v[36:37], v[44:45], v[52:53] op_sel_hi:[1,0]
	v_pk_mul_f32 v[44:45], v[48:49], v[52:53] op_sel_hi:[1,0]
	v_cvt_pk_bf16_f32 v36, v36, v37
	v_cvt_pk_bf16_f32 v37, v38, v39
	s_nop 0
	v_cvt_pk_bf16_f32 v38, v44, v45
	v_cvt_pk_bf16_f32 v39, v42, v43
	global_store_dwordx4 v[40:41], v[36:39], off
	v_add_u32_e32 v40, 0xa0, v128
	v_ashrrev_i32_e32 v41, 31, v40
	v_lshlrev_b64 v[36:37], 6, v[40:41]
	v_lshl_add_u64 v[36:37], s[18:19], 0, v[36:37]
	global_load_dwordx4 v[36:39], v[36:37], off offset:32
	s_waitcnt vmcnt(0)
	v_mov_b32_e32 v42, v37
	v_mov_b32_e32 v43, v38
	v_mov_b32_e32 v37, v39
	v_pk_add_f32 v[36:37], v[42:43], v[36:37]
	s_nop 0
	v_add_f32_e32 v36, v36, v37
	v_fmamk_f32 v36, v36, 0x3b800000, v252
	v_cmp_gt_f32_e32 vcc, s53, v36
	v_mul_f32_e32 v37, 0x4b800000, v36
	s_nop 0
	v_cndmask_b32_e32 v36, v36, v37, vcc
	v_rsq_f32_e32 v36, v36
	s_nop 0
	v_mul_f32_e32 v37, 0x45800000, v36
	v_cndmask_b32_e32 v36, v36, v37, vcc
	v_pk_mul_f32 v[22:23], v[22:23], v[36:37] op_sel_hi:[1,0]
	v_pk_mul_f32 v[20:21], v[20:21], v[36:37] op_sel_hi:[1,0]
	v_pk_mul_f32 v[24:25], v[24:25], v[36:37] op_sel_hi:[1,0]
	v_pk_mul_f32 v[26:27], v[26:27], v[36:37] op_sel_hi:[1,0]
	v_cvt_pk_bf16_f32 v20, v20, v21
	v_cvt_pk_bf16_f32 v21, v22, v23
	v_cvt_pk_bf16_f32 v22, v24, v25
	v_mad_i64_i32 v[24:25], s[16:17], v40, s52, v[130:131]
	v_cvt_pk_bf16_f32 v23, v26, v27
	v_lshl_add_u64 v[26:27], v[24:25], 0, v[132:133]
	v_lshl_add_u64 v[26:27], v[26:27], 0, v[176:177]
	v_lshl_add_u64 v[24:25], v[24:25], 0, v[116:117]
	global_store_dwordx4 v[26:27], v[20:23], off
	v_lshl_add_u64 v[24:25], v[24:25], 0, v[176:177]
	v_pk_mul_f32 v[26:27], v[34:35], v[36:37] op_sel_hi:[1,0]
	v_pk_mul_f32 v[22:23], v[30:31], v[36:37] op_sel_hi:[1,0]
	v_pk_mul_f32 v[20:21], v[28:29], v[36:37] op_sel_hi:[1,0]
	v_pk_mul_f32 v[28:29], v[32:33], v[36:37] op_sel_hi:[1,0]
	v_cvt_pk_bf16_f32 v20, v20, v21
	v_cvt_pk_bf16_f32 v21, v22, v23
	s_nop 0
	v_cvt_pk_bf16_f32 v22, v28, v29
	v_cvt_pk_bf16_f32 v23, v26, v27
	global_store_dwordx4 v[24:25], v[20:23], off
	v_add_u32_e32 v24, 0xb0, v128
	v_ashrrev_i32_e32 v25, 31, v24
	v_lshlrev_b64 v[20:21], 6, v[24:25]
	v_lshl_add_u64 v[20:21], s[18:19], 0, v[20:21]
	global_load_dwordx4 v[20:23], v[20:21], off offset:32
	s_waitcnt vmcnt(0)
	v_mov_b32_e32 v26, v21
	v_mov_b32_e32 v27, v22
	v_mov_b32_e32 v21, v23
	v_pk_add_f32 v[20:21], v[26:27], v[20:21]
	s_nop 0
	v_add_f32_e32 v20, v20, v21
	v_fmamk_f32 v20, v20, 0x3b800000, v252
	v_cmp_gt_f32_e32 vcc, s53, v20
	v_mul_f32_e32 v21, 0x4b800000, v20
	s_nop 0
	v_cndmask_b32_e32 v20, v20, v21, vcc
	v_rsq_f32_e32 v20, v20
	s_nop 0
	v_mul_f32_e32 v21, 0x45800000, v20
	v_cndmask_b32_e32 v20, v20, v21, vcc
	v_pk_mul_f32 v[6:7], v[6:7], v[20:21] op_sel_hi:[1,0]
	v_pk_mul_f32 v[4:5], v[4:5], v[20:21] op_sel_hi:[1,0]
	v_pk_mul_f32 v[8:9], v[8:9], v[20:21] op_sel_hi:[1,0]
	v_pk_mul_f32 v[10:11], v[10:11], v[20:21] op_sel_hi:[1,0]
	v_cvt_pk_bf16_f32 v4, v4, v5
	v_cvt_pk_bf16_f32 v5, v6, v7
	v_cvt_pk_bf16_f32 v6, v8, v9
	v_mad_i64_i32 v[8:9], s[16:17], v24, s52, v[130:131]
	v_cvt_pk_bf16_f32 v7, v10, v11
	v_lshl_add_u64 v[10:11], v[8:9], 0, v[132:133]
	v_lshl_add_u64 v[10:11], v[10:11], 0, v[176:177]
	v_lshl_add_u64 v[8:9], v[8:9], 0, v[116:117]
	global_store_dwordx4 v[10:11], v[4:7], off
	v_lshl_add_u64 v[8:9], v[8:9], 0, v[176:177]
	s_andn2_b64 vcc, exec, s[4:5]
	v_pk_mul_f32 v[6:7], v[14:15], v[20:21] op_sel_hi:[1,0]
	v_pk_mul_f32 v[4:5], v[12:13], v[20:21] op_sel_hi:[1,0]
	s_mov_b32 s16, s8
	v_readlane_b32 s4, v254, 46
	v_pk_mul_f32 v[10:11], v[18:19], v[20:21] op_sel_hi:[1,0]
	v_pk_mul_f32 v[12:13], v[16:17], v[20:21] op_sel_hi:[1,0]
	v_cvt_pk_bf16_f32 v4, v4, v5
	v_cvt_pk_bf16_f32 v5, v6, v7
	v_readlane_b32 s5, v254, 47
	v_cvt_pk_bf16_f32 v6, v12, v13
	v_cvt_pk_bf16_f32 v7, v10, v11
	global_store_dwordx4 v[8:9], v[4:7], off
	s_cbranch_vccz .LBB0_174
